# attention hot loops hand-scheduled (prefetch ring, interleaved softmax), lazy rescale threshold 8 log2 units; PC1 epilogue loads batched
# speedup vs baseline: 1.0240x; 1.0240x over previous
.LBB0_1152:
	s_lshr_b32 s22, s62, 6
	s_lshl_b32 s18, s22, 11
	s_or_b32 s20, s18, 0x1000
	s_lshl_b32 s18, s62, 7
	s_and_b32 s18, s18, 0x780
	s_or_b32 s21, s20, s18
	s_bfe_u32 s24, s62, 0x10005
	s_lshl_b32 s18, s21, 9
	s_lshl_b32 s21, s21, 10
	s_add_u32 s70, s47, s21
	s_addc_u32 s71, s48, 0
	s_lshl_b32 s23, s62, 3
	s_lshl_b32 s21, s24, 8
	s_and_b32 s23, s23, 0x80
	s_or_b32 s65, s21, s23
	s_or_b32 s66, s65, 64
	s_lshl_b32 s20, s20, 8
	s_add_u32 s20, s49, s20
	s_addc_u32 s21, s50, 0
	s_lshl_b32 s23, s24, 7
	s_add_u32 s20, s20, s23
	s_addc_u32 s21, s21, 0
	s_lshl_b32 s26, s22, 16
	s_or_b32 s63, s26, s3
	s_add_u32 s26, s31, s63
	s_addc_u32 s27, s34, 0
	s_add_u32 s26, s26, s23
	s_addc_u32 s27, s27, 0
	s_lshl_b32 s22, s22, 19
	s_add_u32 s22, s55, s22
	s_addc_u32 s23, s56, 0
	s_lshl_b32 s64, s24, 18
	s_add_u32 s22, s22, s64
	s_addc_u32 s23, s23, 0
	s_add_u32 s63, s35, s63
	s_addc_u32 s64, s36, 0
	s_lshl_b32 s24, s24, 15
	v_mov_b32_e32 v12, v244
	s_add_u32 s63, s63, s24
	s_addc_u32 s64, s64, 0
	v_readfirstlane_b32 s24, v12
	s_lshr_b32 s68, s24, 1
	v_and_b32_e32 v1, 31, v12
	s_and_b32 s68, s68, 0x60
	s_waitcnt vmcnt(1)
	v_mul_u32_u24_e32 v139, 0x90, v1
	v_or_b32_e32 v1, s68, v1
	s_cmpk_lt_u32 s24, 0x100
	v_lshlrev_b32_e32 v128, 10, v1
	s_cselect_b32 s24, s65, s66
	v_bfe_u32 v0, v12, 5, 1
	v_lshl_add_u64 v[2:3], s[70:71], 0, v[128:129]
	s_lshl_b32 s68, s24, 1
	v_lshlrev_b32_e32 v138, 3, v0
	v_lshlrev_b32_e32 v0, 4, v0
	v_lshlrev_b32_e32 v140, 9, v1
	v_lshl_add_u64 v[2:3], v[2:3], 0, s[68:69]
	v_mov_b32_e32 v1, v129
	v_lshl_add_u64 v[2:3], v[2:3], 0, v[0:1]
	v_ashrrev_i32_e32 v1, 31, v12
	v_lshrrev_b32_e32 v1, 29, v1
	v_add_u32_e32 v1, v12, v1
	v_ashrrev_i32_e32 v10, 3, v1
	v_and_b32_e32 v1, -8, v1
	v_sub_u32_e32 v1, v12, v1
	v_ashrrev_i32_e32 v11, 31, v10
	global_load_dwordx4 v[108:111], v[2:3], off
	global_load_dwordx4 v[104:107], v[2:3], off offset:32
	global_load_dwordx4 v[100:103], v[2:3], off offset:64
	global_load_dwordx4 v[96:99], v[2:3], off offset:96
	v_lshlrev_b64 v[2:3], 8, v[10:11]
	s_waitcnt vmcnt(4)
	v_lshlrev_b32_e32 v144, 3, v1
	v_ashrrev_i32_e32 v146, 3, v12
	v_lshl_add_u64 v[2:3], s[20:21], 0, v[2:3]
	v_ashrrev_i32_e32 v145, 31, v144
	v_ashrrev_i32_e32 v147, 31, v146
	v_lshlrev_b32_e32 v8, 3, v12
	v_lshl_add_u64 v[58:59], v[144:145], 1, v[2:3]
	v_lshlrev_b64 v[6:7], 12, v[146:147]
	v_and_b32_e32 v56, 56, v8
	global_load_dwordx4 v[2:5], v[58:59], off
	v_lshl_add_u64 v[6:7], s[22:23], 0, v[6:7]
	v_lshlrev_b32_e32 v128, 1, v56
	v_lshl_add_u64 v[60:61], v[6:7], 0, v[128:129]
	global_load_dwordx4 v[6:9], v[60:61], off
	s_movk_i32 s65, 0x90
	v_mul_lo_u32 v150, v10, s65
	v_lshlrev_b32_e32 v151, 4, v1
	v_add3_u32 v57, 0, v150, v151
	v_mul_lo_u32 v152, v146, s65
	v_lshlrev_b32_e32 v1, 4, v12
	s_movk_i32 s65, 0x4000
	v_and_b32_e32 v153, 0x70, v1
	v_add3_u32 v62, 0, v152, v153
	v_add3_u32 v154, 0, v0, v139
	s_mov_b32 s68, s69
	v_lshlrev_b64 v[142:143], 7, v[10:11]
	s_mov_b32 s70, s69
	s_mov_b32 s71, s69
	s_mov_b32 s72, s69
	s_mov_b32 s73, s69
	s_mov_b32 s74, s69
	s_mov_b32 s75, s69
	s_mov_b32 s76, s69
	s_mov_b32 s77, s69
	s_mov_b32 s78, s69
	s_mov_b32 s79, s69
	s_mov_b32 s80, s69
	s_mov_b32 s81, s69
	s_mov_b32 s82, s69
	s_mov_b32 s83, s69
	s_mov_b32 s19, s69
	s_mov_b32 s25, 3
	s_mov_b32 s84, 1
	s_mov_b32 s66, 2
	s_waitcnt vmcnt(1)
	ds_write_b128 v57, v[2:5]
	v_add_co_u32_e32 v2, vcc, s65, v58
	s_mov_b32 s65, 0
	s_nop 0
	v_addc_co_u32_e32 v3, vcc, 0, v59, vcc
	s_waitcnt vmcnt(0)
	ds_write_b128 v62, v[6:9] offset:17408
	s_waitcnt lgkmcnt(0)
	s_barrier
	global_load_dwordx4 v[48:51], v[2:3], off
	global_load_dwordx4 v[52:55], v[60:61], off offset:128
	ds_read_b128 v[32:35], v154 offset:4608
	ds_read_b128 v[16:19], v154
	ds_read_b128 v[64:67], v154 offset:32
	ds_read_b128 v[68:71], v154 offset:4640
	s_waitcnt lgkmcnt(2)
	v_mfma_f32_32x32x16_bf16 v[16:31], v[16:19], v[108:111], 0
	v_mov_b64_e32 v[0:1], s[68:69]
	v_mov_b64_e32 v[14:15], s[82:83]
	v_mov_b64_e32 v[2:3], s[70:71]
	v_mov_b64_e32 v[4:5], s[72:73]
	v_mov_b64_e32 v[6:7], s[74:75]
	v_mov_b64_e32 v[8:9], s[76:77]
	v_mov_b64_e32 v[10:11], s[78:79]
	v_mfma_f32_32x32x16_bf16 v[32:47], v[32:35], v[108:111], 0
	v_mov_b64_e32 v[12:13], s[80:81]
	v_readlane_b32 s82, v254, 47
	v_readlane_b32 s83, v254, 48
	s_waitcnt lgkmcnt(1)
	v_mfma_f32_32x32x16_bf16 v[16:31], v[64:67], v[104:107], v[16:31]
	s_waitcnt lgkmcnt(0)
	v_mfma_f32_32x32x16_bf16 v[32:47], v[68:71], v[104:107], v[32:47]
	ds_read_b128 v[64:67], v154 offset:4672
	ds_read_b128 v[68:71], v154 offset:64
	s_waitcnt lgkmcnt(0)
	v_mfma_f32_32x32x16_bf16 v[16:31], v[68:71], v[100:103], v[16:31]
	v_mfma_f32_32x32x16_bf16 v[32:47], v[64:67], v[100:103], v[32:47]
	ds_read_b128 v[64:67], v154 offset:4704
	ds_read_b128 v[68:71], v154 offset:96
	s_waitcnt lgkmcnt(0)
	v_mfma_f32_32x32x16_bf16 v[16:31], v[68:71], v[96:99], v[16:31]
	v_mfma_f32_32x32x16_bf16 v[32:47], v[64:67], v[96:99], v[32:47]
	s_nop 15
	s_nop 7
	v_and_b32_e32 v65, 64, v248
	v_max3_f32 v63, v16, v17, v32
	v_xor_b32_e32 v64, 32, v248
	v_max3_f32 v63, v63, v33, v18
	v_add_u32_e32 v65, 64, v65
	v_max3_f32 v63, v63, v34, v34
	v_cmp_lt_i32_e32 vcc, v64, v65
	v_max3_f32 v63, v63, v19, v35
	s_waitcnt vmcnt(1)
	ds_write_b128 v57, v[48:51] offset:36864
	s_waitcnt vmcnt(0)
	ds_write_b128 v62, v[52:55] offset:54272
	v_max3_f32 v63, v63, v20, v36
	v_cndmask_b32_e32 v64, v248, v64, vcc
	v_max3_f32 v63, v63, v21, v37
	v_lshlrev_b32_e32 v141, 2, v64
	v_max3_f32 v63, v63, v22, v38
	s_waitcnt lgkmcnt(0)
	v_max3_f32 v63, v63, v23, v39
	s_barrier
	v_max3_f32 v63, v63, v24, v40
	s_nop 0
	v_max3_f32 v63, v63, v25, v41
	s_nop 0
	v_max3_f32 v63, v63, v26, v42
	s_nop 0
	v_max3_f32 v63, v63, v27, v43
	s_nop 0
	v_max3_f32 v63, v63, v28, v44
	s_nop 0
	v_max3_f32 v63, v63, v29, v45
	s_nop 0
	v_max3_f32 v63, v63, v30, v46
	s_nop 0
	v_max3_f32 v63, v63, v31, v47
	ds_bpermute_b32 v64, v141, v63
	v_max_f32_e32 v63, v63, v63
	s_waitcnt lgkmcnt(0)
	v_max_f32_e32 v64, v64, v64
	v_max_f32_e32 v65, v63, v64
	v_sub_f32_e32 v16, v16, v65
	v_sub_f32_e32 v32, v32, v65
	v_sub_f32_e32 v17, v17, v65
	v_sub_f32_e32 v33, v33, v65
	v_exp_f32_e32 v74, v16
	v_exp_f32_e32 v75, v32
	v_sub_f32_e32 v18, v18, v65
	v_sub_f32_e32 v34, v34, v65
	v_exp_f32_e32 v76, v17
	v_exp_f32_e32 v77, v33
	v_exp_f32_e32 v78, v18
	v_exp_f32_e32 v79, v34
	v_add_f32_e32 v16, v75, v74
	v_add_f32_e32 v16, 0, v16
	v_add_f32_e32 v17, v77, v76
	v_sub_f32_e32 v19, v19, v65
	v_sub_f32_e32 v35, v35, v65
	v_sub_f32_e32 v20, v20, v65
	v_sub_f32_e32 v36, v36, v65
	v_add_f32_e32 v16, v17, v16
	v_add_f32_e32 v17, v79, v78
	v_sub_f32_e32 v64, v23, v65
	v_add_f32_e32 v23, v17, v16
	v_exp_f32_e32 v17, v19
	v_exp_f32_e32 v19, v35
	v_exp_f32_e32 v16, v20
	v_exp_f32_e32 v18, v36
	v_sub_f32_e32 v63, v21, v65
	v_sub_f32_e32 v68, v26, v65
	v_cvt_pk_bf16_f32 v135, v78, v17
	v_pk_add_f32 v[20:21], v[18:19], v[16:17]
	v_sub_f32_e32 v37, v37, v65
	v_add_f32_e32 v21, v21, v23
	v_add_f32_e32 v26, v20, v21
	v_exp_f32_e32 v21, v63
	v_sub_f32_e32 v22, v22, v65
	v_sub_f32_e32 v38, v38, v65
	v_exp_f32_e32 v23, v37
	v_cvt_pk_bf16_f32 v136, v16, v21
	v_add_co_u32_e32 v16, vcc, 0x8000, v58
	v_exp_f32_e32 v20, v22
	s_nop 0
	v_addc_co_u32_e32 v17, vcc, 0, v59, vcc
	global_load_dwordx4 v[116:119], v[16:17], off
	global_load_dwordx4 v[124:127], v[60:61], off offset:256
	v_exp_f32_e32 v22, v38
	v_sub_f32_e32 v66, v24, v65
	v_sub_f32_e32 v67, v25, v65
	v_sub_f32_e32 v39, v39, v65
	v_pk_add_f32 v[24:25], v[22:23], v[20:21]
	v_sub_f32_e32 v40, v40, v65
	v_add_f32_e32 v25, v25, v26
	v_sub_f32_e32 v69, v27, v65
	v_sub_f32_e32 v72, v30, v65
	v_add_f32_e32 v30, v24, v25
	v_exp_f32_e32 v25, v64
	v_exp_f32_e32 v27, v39
	v_exp_f32_e32 v24, v66
	v_exp_f32_e32 v26, v40
	v_sub_f32_e32 v70, v28, v65
	v_sub_f32_e32 v71, v29, v65
	v_sub_f32_e32 v41, v41, v65
	v_pk_add_f32 v[28:29], v[26:27], v[24:25]
	v_sub_f32_e32 v42, v42, v65
	v_add_f32_e32 v29, v29, v30
	v_sub_f32_e32 v73, v31, v65
	v_add_f32_e32 v34, v28, v29
	v_exp_f32_e32 v29, v67
	v_exp_f32_e32 v31, v41
	v_exp_f32_e32 v28, v68
	v_exp_f32_e32 v30, v42
	v_sub_f32_e32 v43, v43, v65
	v_sub_f32_e32 v44, v44, v65
	v_exp_f32_e32 v35, v69
	v_pk_add_f32 v[32:33], v[30:31], v[28:29]
	v_exp_f32_e32 v37, v43
	v_add_f32_e32 v33, v33, v34
	v_exp_f32_e32 v34, v70
	v_exp_f32_e32 v36, v44
	v_sub_f32_e32 v45, v45, v65
	v_sub_f32_e32 v46, v46, v65
	v_add_f32_e32 v38, v32, v33
	v_pk_add_f32 v[32:33], v[36:37], v[34:35]
	v_exp_f32_e32 v39, v71
	v_add_f32_e32 v33, v33, v38
	v_exp_f32_e32 v41, v45
	v_exp_f32_e32 v38, v72
	v_exp_f32_e32 v40, v46
	v_add_f32_e32 v42, v32, v33
	v_sub_f32_e32 v47, v47, v65
	v_or_b32_e32 v16, v139, v138
	v_pk_add_f32 v[32:33], v[40:41], v[38:39]
	v_cvt_pk_bf16_f32 v137, v20, v25
	v_add_f32_e32 v33, v33, v42
	v_add_f32_e32 v128, v32, v33
	v_exp_f32_e32 v33, v73
	v_exp_f32_e32 v42, v47
	v_cvt_pk_bf16_f32 v121, v79, v19
	v_cvt_pk_bf16_f32 v122, v18, v23
	v_cvt_pk_bf16_f32 v123, v22, v27
	v_add_f32_e32 v64, v42, v33
	v_pk_add_f32 v[148:149], v[64:65], v[128:129]
	v_cvt_pk_bf16_f32 v130, v24, v29
	v_xor_b32_e32 v32, 0x80000000, v149
	v_cvt_pk_bf16_f32 v131, v28, v35
	v_cvt_pk_bf16_f32 v112, v26, v31
	v_cvt_pk_bf16_f32 v113, v30, v37
	v_add_u32_e32 v155, 0, v16
	v_mov_b64_e32 v[30:31], v[14:15]
	v_cvt_pk_bf16_f32 v134, v74, v76
	v_cvt_pk_bf16_f32 v120, v75, v77
	v_cvt_pk_bf16_f32 v132, v34, v39
	v_cvt_pk_bf16_f32 v133, v38, v33
	v_cvt_pk_bf16_f32 v114, v36, v41
	v_cvt_pk_bf16_f32 v115, v40, v42
	v_lshlrev_b32_e32 v128, 1, v56
	v_mov_b64_e32 v[28:29], v[12:13]
	v_mov_b64_e32 v[26:27], v[10:11]
	v_mov_b64_e32 v[24:25], v[8:9]
	v_mov_b64_e32 v[22:23], v[6:7]
	v_mov_b64_e32 v[20:21], v[4:5]
	v_mov_b64_e32 v[18:19], v[2:3]
	v_mov_b64_e32 v[16:17], v[0:1]
	v_mov_b32_e32 v33, v32
	v_mov_b32_e32 v34, v32
	v_mov_b32_e32 v35, v32
	v_mov_b32_e32 v36, v32
	v_mov_b32_e32 v37, v32
	v_mov_b32_e32 v38, v32
	v_mov_b32_e32 v39, v32
	v_mov_b32_e32 v40, v32
	v_mov_b32_e32 v41, v32
	v_mov_b32_e32 v42, v32
	v_mov_b32_e32 v43, v32
	v_mov_b32_e32 v44, v32
	v_mov_b32_e32 v45, v32
	v_mov_b32_e32 v46, v32
	v_mov_b32_e32 v47, v32
	v_mov_b64_e32 v[48:49], v[32:33]
	v_mov_b64_e32 v[50:51], v[34:35]
	v_mov_b64_e32 v[52:53], v[36:37]
	v_mov_b64_e32 v[54:55], v[38:39]
	v_mov_b64_e32 v[56:57], v[40:41]
	v_mov_b64_e32 v[58:59], v[42:43]
	v_mov_b64_e32 v[60:61], v[44:45]
	v_mov_b64_e32 v[62:63], v[46:47]
.LBB0_1153:
	s_mul_i32 s70, s84, 0x9000
	v_add_u32_e32 v208, s70, v154
	s_mov_b32 s71, s65
	s_mul_i32 s68, s71, 0x9000
	s_mov_b32 s65, s84
	v_add_u32_e32 v209, s68, v155
	v_add_u32_e32 v210, 0x4000, v209
	v_add_u32_e32 v211, 0x5000, v209
	ds_read_b128 v[156:159], v208
	ds_read_b128 v[160:163], v208 offset:4608
	ds_read_b128 v[164:167], v208 offset:32
	ds_read_b128 v[168:171], v208 offset:4640
	ds_read_b128 v[172:175], v208 offset:64
	ds_read_b128 v[176:179], v208 offset:4672
	ds_read_b128 v[184:187], v208 offset:96
	ds_read_b128 v[188:191], v208 offset:4704
	ds_read2_b64 v[192:195], v210 offset0:128 offset1:130
	ds_read2_b64 v[196:199], v211 offset0:192 offset1:194
	ds_read2_b64 v[200:203], v210 offset0:132 offset1:134
	ds_read2_b64 v[204:207], v211 offset0:196 offset1:198
	s_waitcnt lgkmcnt(11)
	v_mfma_f32_32x32x16_bf16 v[64:79], v[156:159], v[108:111], v[32:47]
	ds_read2_b64 v[156:159], v210 offset0:136 offset1:138
	s_mul_i32 s72, s66, 0x9000
	s_add_i32 s73, s72, 0
	v_add3_u32 v218, s73, v150, v151
	v_add3_u32 v219, s73, v152, v153
	s_waitcnt lgkmcnt(11)
	v_mfma_f32_32x32x16_bf16 v[80:95], v[160:163], v[108:111], v[32:47]
	ds_read2_b64 v[160:163], v211 offset0:200 offset1:202
	s_waitcnt vmcnt(0)
	ds_write_b128 v218, v[116:119]
	ds_write_b128 v219, v[124:127] offset:17408
	s_waitcnt lgkmcnt(13)
	v_mfma_f32_32x32x16_bf16 v[64:79], v[164:167], v[104:107], v[64:79]
	ds_read2_b64 v[164:167], v210 offset0:140 offset1:142
	s_waitcnt lgkmcnt(13)
	v_mfma_f32_32x32x16_bf16 v[80:95], v[168:171], v[104:107], v[80:95]
	ds_read2_b64 v[168:171], v211 offset0:204 offset1:206
	s_waitcnt lgkmcnt(13)
	v_mfma_f32_32x32x16_bf16 v[64:79], v[172:175], v[100:103], v[64:79]
	s_waitcnt lgkmcnt(12)
	v_mfma_f32_32x32x16_bf16 v[80:95], v[176:179], v[100:103], v[80:95]
	s_waitcnt lgkmcnt(11)
	v_mfma_f32_32x32x16_bf16 v[64:79], v[184:187], v[96:99], v[64:79]
	s_waitcnt lgkmcnt(10)
	v_mfma_f32_32x32x16_bf16 v[80:95], v[188:191], v[96:99], v[80:95]
	s_waitcnt lgkmcnt(9)
	v_mfma_f32_32x32x16_bf16 v[16:31], v[192:195], v[134:137], v[16:31]
	s_waitcnt lgkmcnt(8)
	v_mfma_f32_32x32x16_bf16 v[0:15], v[196:199], v[134:137], v[0:15]
	s_add_i32 s68, s25, -2
	s_cmp_gt_u32 s68, 33
	s_cbranch_scc1 .Lag_nogl
	s_cmp_lt_u32 s68, 30
	s_cselect_b64 s[74:75], -1, 0
	s_and_b64 s[76:77], s[74:75], exec
	s_cselect_b32 s68, 0, 0xffffffe0
	s_add_i32 s68, s68, s25
	s_and_b64 s[76:77], s[74:75], exec
	s_cselect_b32 s73, s21, s27
	s_cselect_b32 s78, s20, s26
	s_lshl_b64 s[76:77], s[68:69], 14
	s_add_u32 s76, s78, s76
	s_addc_u32 s77, s73, s77
	s_and_b64 s[78:79], s[74:75], exec
	s_cselect_b32 s73, s23, s64
	s_cselect_b32 s80, s22, s63
	s_lshl_b32 s68, s68, 6
	s_lshl_b64 s[78:79], s[68:69], 1
	s_add_u32 s78, s80, s78
	s_addc_u32 s79, s73, s79
	v_lshl_add_u64 v[222:223], v[142:143], 1, s[76:77]
	s_and_b64 s[74:75], s[74:75], exec
	v_lshl_add_u64 v[222:223], v[144:145], 1, v[222:223]
	s_cselect_b32 s68, 11, 8
	global_load_dwordx4 v[116:119], v[222:223], off
	v_lshlrev_b64 v[222:223], s68, v[146:147]
	v_lshl_add_u64 v[222:223], v[222:223], 1, s[78:79]
	v_lshl_add_u64 v[222:223], v[222:223], 0, v[128:129]
	global_load_dwordx4 v[124:127], v[222:223], off
.Lag_nogl:
	s_waitcnt lgkmcnt(7)
	v_mfma_f32_32x32x16_bf16 v[16:31], v[200:203], v[130:133], v[16:31]
	s_waitcnt lgkmcnt(6)
	v_mfma_f32_32x32x16_bf16 v[0:15], v[204:207], v[130:133], v[0:15]
	s_waitcnt lgkmcnt(5)
	v_mfma_f32_32x32x16_bf16 v[16:31], v[156:159], v[120:123], v[16:31]
	s_waitcnt lgkmcnt(4)
	v_mfma_f32_32x32x16_bf16 v[0:15], v[160:163], v[120:123], v[0:15]
	v_max3_f32 v212, v64, v80, v68
	v_max3_f32 v213, v65, v81, v69
	v_max3_f32 v214, v66, v82, v70
	v_max3_f32 v215, v67, v83, v71
	v_max3_f32 v212, v212, v84, v72
	v_max3_f32 v213, v213, v85, v73
	v_max3_f32 v214, v214, v86, v74
	v_max3_f32 v215, v215, v87, v75
	s_waitcnt lgkmcnt(1)
	v_mfma_f32_32x32x16_bf16 v[16:31], v[164:167], v[112:115], v[16:31]
	v_max3_f32 v212, v212, v88, v76
	v_max3_f32 v213, v213, v89, v77
	v_max3_f32 v214, v214, v90, v78
	v_max3_f32 v215, v215, v91, v79
	v_max_f32_e32 v212, v212, v92
	v_max_f32_e32 v213, v213, v93
	v_max_f32_e32 v214, v214, v94
	v_max_f32_e32 v215, v215, v95
	s_waitcnt lgkmcnt(0)
	v_mfma_f32_32x32x16_bf16 v[0:15], v[168:171], v[112:115], v[0:15]
	v_max3_f32 v212, v212, v213, v214
	v_max_f32_e32 v212, v212, v215
	v_mov_b32_e32 v216, v212
	v_mov_b32_e32 v217, v212
	s_nop 1
	v_permlane32_swap_b32_e32 v216, v217
	v_max_f32_e32 v212, v216, v217
	v_cmp_lt_f32_e32 vcc, 0x41000000, v212
	s_cbranch_vccz .Lag_common
	s_nop 7
	s_nop 3
	v_max_f32_e32 v32, v212, v212
	v_max_f32_e32 v32, 0, v32
	v_exp_f32_e64 v112, -v32
	v_add_f32_e32 v149, v149, v32
	v_xor_b32_e32 v48, 0x80000000, v149
	v_pk_add_f32 v[64:65], v[64:65], v[32:33] op_sel_hi:[1,0] neg_lo:[0,1] neg_hi:[0,1]
	v_pk_add_f32 v[80:81], v[80:81], v[32:33] op_sel_hi:[1,0] neg_lo:[0,1] neg_hi:[0,1]
	v_pk_add_f32 v[66:67], v[66:67], v[32:33] op_sel_hi:[1,0] neg_lo:[0,1] neg_hi:[0,1]
	v_pk_add_f32 v[82:83], v[82:83], v[32:33] op_sel_hi:[1,0] neg_lo:[0,1] neg_hi:[0,1]
	v_pk_add_f32 v[68:69], v[68:69], v[32:33] op_sel_hi:[1,0] neg_lo:[0,1] neg_hi:[0,1]
	v_pk_add_f32 v[84:85], v[84:85], v[32:33] op_sel_hi:[1,0] neg_lo:[0,1] neg_hi:[0,1]
	v_pk_add_f32 v[70:71], v[70:71], v[32:33] op_sel_hi:[1,0] neg_lo:[0,1] neg_hi:[0,1]
	v_pk_add_f32 v[86:87], v[86:87], v[32:33] op_sel_hi:[1,0] neg_lo:[0,1] neg_hi:[0,1]
	v_pk_add_f32 v[72:73], v[72:73], v[32:33] op_sel_hi:[1,0] neg_lo:[0,1] neg_hi:[0,1]
	v_pk_add_f32 v[88:89], v[88:89], v[32:33] op_sel_hi:[1,0] neg_lo:[0,1] neg_hi:[0,1]
	v_pk_add_f32 v[74:75], v[74:75], v[32:33] op_sel_hi:[1,0] neg_lo:[0,1] neg_hi:[0,1]
	v_pk_add_f32 v[90:91], v[90:91], v[32:33] op_sel_hi:[1,0] neg_lo:[0,1] neg_hi:[0,1]
	v_pk_add_f32 v[76:77], v[76:77], v[32:33] op_sel_hi:[1,0] neg_lo:[0,1] neg_hi:[0,1]
	v_pk_add_f32 v[92:93], v[92:93], v[32:33] op_sel_hi:[1,0] neg_lo:[0,1] neg_hi:[0,1]
	v_pk_add_f32 v[78:79], v[78:79], v[32:33] op_sel_hi:[1,0] neg_lo:[0,1] neg_hi:[0,1]
	v_pk_add_f32 v[94:95], v[94:95], v[32:33] op_sel_hi:[1,0] neg_lo:[0,1] neg_hi:[0,1]
	v_mov_b32_e32 v49, v48
	v_mov_b32_e32 v50, v48
	v_mov_b32_e32 v51, v48
	v_mov_b32_e32 v52, v48
	v_mov_b32_e32 v53, v48
	v_mov_b32_e32 v54, v48
	v_mov_b32_e32 v55, v48
	v_mov_b32_e32 v56, v48
	v_mov_b32_e32 v57, v48
	v_mov_b32_e32 v58, v48
	v_mov_b32_e32 v59, v48
	v_mov_b32_e32 v60, v48
	v_mov_b32_e32 v61, v48
	v_mov_b32_e32 v62, v48
	v_mov_b32_e32 v63, v48
	v_mov_b32_e32 v32, v48
	v_mov_b32_e32 v33, v48
	v_mov_b32_e32 v34, v48
	v_mov_b32_e32 v35, v48
	v_mov_b32_e32 v36, v48
	v_mov_b32_e32 v37, v48
	v_mov_b32_e32 v38, v48
	v_mov_b32_e32 v39, v48
	v_mov_b32_e32 v40, v48
	v_mov_b32_e32 v41, v48
	v_mov_b32_e32 v42, v48
	v_mov_b32_e32 v43, v48
	v_mov_b32_e32 v44, v48
	v_mov_b32_e32 v45, v48
	v_mov_b32_e32 v46, v48
	v_mov_b32_e32 v47, v48
	v_cmp_neq_f32_e32 vcc, 1.0, v112
	s_cbranch_vccz .Lag_rjoin
	v_pk_mul_f32 v[30:31], v[30:31], v[112:113] op_sel_hi:[1,0]
	v_pk_mul_f32 v[28:29], v[28:29], v[112:113] op_sel_hi:[1,0]
	v_pk_mul_f32 v[26:27], v[26:27], v[112:113] op_sel_hi:[1,0]
	v_pk_mul_f32 v[24:25], v[24:25], v[112:113] op_sel_hi:[1,0]
	v_pk_mul_f32 v[22:23], v[22:23], v[112:113] op_sel_hi:[1,0]
	v_pk_mul_f32 v[20:21], v[20:21], v[112:113] op_sel_hi:[1,0]
	v_pk_mul_f32 v[18:19], v[18:19], v[112:113] op_sel_hi:[1,0]
	v_pk_mul_f32 v[16:17], v[16:17], v[112:113] op_sel_hi:[1,0]
	v_pk_mul_f32 v[14:15], v[14:15], v[112:113] op_sel_hi:[1,0]
	v_pk_mul_f32 v[12:13], v[12:13], v[112:113] op_sel_hi:[1,0]
	v_pk_mul_f32 v[10:11], v[10:11], v[112:113] op_sel_hi:[1,0]
	v_pk_mul_f32 v[8:9], v[8:9], v[112:113] op_sel_hi:[1,0]
	v_pk_mul_f32 v[6:7], v[6:7], v[112:113] op_sel_hi:[1,0]
	v_pk_mul_f32 v[4:5], v[4:5], v[112:113] op_sel_hi:[1,0]
	v_pk_mul_f32 v[2:3], v[2:3], v[112:113] op_sel_hi:[1,0]
	v_pk_mul_f32 v[0:1], v[0:1], v[112:113] op_sel_hi:[1,0]
.Lag_rjoin:
	v_exp_f32_e32 v64, v64
	v_exp_f32_e32 v80, v80
	v_exp_f32_e32 v113, v65
	v_exp_f32_e32 v81, v81
	v_exp_f32_e32 v66, v66
	v_exp_f32_e32 v82, v82
	v_exp_f32_e32 v67, v67
	v_exp_f32_e32 v83, v83
	v_add_f32_e32 v65, v80, v64
	v_exp_f32_e32 v68, v68
	v_exp_f32_e32 v84, v84
	v_add_f32_e32 v65, 0, v65
	v_add_f32_e32 v114, v81, v113
	v_exp_f32_e32 v69, v69
	v_exp_f32_e32 v85, v85
	v_add_f32_e32 v65, v114, v65
	v_add_f32_e32 v114, v82, v66
	v_exp_f32_e32 v70, v70
	v_exp_f32_e32 v86, v86
	v_add_f32_e32 v65, v114, v65
	v_add_f32_e32 v114, v83, v67
	v_exp_f32_e32 v71, v71
	v_exp_f32_e32 v87, v87
	v_add_f32_e32 v65, v114, v65
	v_add_f32_e32 v114, v84, v68
	v_exp_f32_e32 v72, v72
	v_exp_f32_e32 v88, v88
	v_add_f32_e32 v65, v114, v65
	v_add_f32_e32 v114, v85, v69
	v_exp_f32_e32 v73, v73
	v_exp_f32_e32 v89, v89
	v_add_f32_e32 v65, v114, v65
	v_add_f32_e32 v114, v86, v70
	v_exp_f32_e32 v74, v74
	v_exp_f32_e32 v90, v90
	v_add_f32_e32 v65, v114, v65
	v_add_f32_e32 v114, v87, v71
	v_exp_f32_e32 v75, v75
	v_exp_f32_e32 v91, v91
	v_add_f32_e32 v65, v114, v65
	v_add_f32_e32 v114, v88, v72
	v_exp_f32_e32 v76, v76
	v_exp_f32_e32 v92, v92
	v_add_f32_e32 v65, v114, v65
	v_add_f32_e32 v114, v89, v73
	v_exp_f32_e32 v77, v77
	v_exp_f32_e32 v93, v93
	v_add_f32_e32 v65, v114, v65
	v_add_f32_e32 v114, v90, v74
	v_exp_f32_e32 v78, v78
	v_exp_f32_e32 v94, v94
	v_add_f32_e32 v65, v114, v65
	v_add_f32_e32 v114, v91, v75
	v_exp_f32_e32 v79, v79
	v_exp_f32_e32 v95, v95
	v_add_f32_e32 v65, v114, v65
	v_add_f32_e32 v114, v92, v76
	v_add_f32_e32 v65, v114, v65
	v_add_f32_e32 v114, v93, v77
	v_add_f32_e32 v65, v114, v65
	v_add_f32_e32 v114, v94, v78
	v_add_f32_e32 v65, v114, v65
	v_add_f32_e32 v114, v95, v79
	v_add_f32_e32 v65, v114, v65
	v_fmac_f32_e32 v65, v148, v112
	v_cvt_pk_bf16_f32 v134, v64, v113
	v_cvt_pk_bf16_f32 v135, v66, v67
	v_cvt_pk_bf16_f32 v136, v68, v69
	v_cvt_pk_bf16_f32 v137, v70, v71
	v_cvt_pk_bf16_f32 v120, v80, v81
	v_cvt_pk_bf16_f32 v121, v82, v83
	v_cvt_pk_bf16_f32 v122, v84, v85
	v_cvt_pk_bf16_f32 v123, v86, v87
	v_cvt_pk_bf16_f32 v130, v72, v73
	v_cvt_pk_bf16_f32 v131, v74, v75
	v_cvt_pk_bf16_f32 v132, v76, v77
	v_cvt_pk_bf16_f32 v133, v78, v79
	v_cvt_pk_bf16_f32 v112, v88, v89
	v_cvt_pk_bf16_f32 v113, v90, v91
	v_cvt_pk_bf16_f32 v114, v92, v93
	v_cvt_pk_bf16_f32 v115, v94, v95
	s_branch .Lag_join
.Lag_common:
	v_exp_f32_e32 v64, v64
	v_exp_f32_e32 v80, v80
	v_exp_f32_e32 v113, v65
	v_exp_f32_e32 v81, v81
	v_exp_f32_e32 v66, v66
	v_exp_f32_e32 v82, v82
	v_exp_f32_e32 v67, v67
	v_exp_f32_e32 v83, v83
	v_add_f32_e32 v65, v80, v64
	v_exp_f32_e32 v68, v68
	v_exp_f32_e32 v84, v84
	v_add_f32_e32 v65, 0, v65
	v_add_f32_e32 v114, v81, v113
	v_exp_f32_e32 v69, v69
	v_exp_f32_e32 v85, v85
	v_add_f32_e32 v65, v114, v65
	v_add_f32_e32 v114, v82, v66
	v_exp_f32_e32 v70, v70
	v_exp_f32_e32 v86, v86
	v_add_f32_e32 v65, v114, v65
	v_add_f32_e32 v114, v83, v67
	v_exp_f32_e32 v71, v71
	v_exp_f32_e32 v87, v87
	v_add_f32_e32 v65, v114, v65
	v_add_f32_e32 v114, v84, v68
	v_exp_f32_e32 v72, v72
	v_exp_f32_e32 v88, v88
	v_add_f32_e32 v65, v114, v65
	v_add_f32_e32 v114, v85, v69
	v_exp_f32_e32 v73, v73
	v_exp_f32_e32 v89, v89
	v_add_f32_e32 v65, v114, v65
	v_add_f32_e32 v114, v86, v70
	v_exp_f32_e32 v74, v74
	v_exp_f32_e32 v90, v90
	v_add_f32_e32 v65, v114, v65
	v_add_f32_e32 v114, v87, v71
	v_exp_f32_e32 v75, v75
	v_exp_f32_e32 v91, v91
	v_add_f32_e32 v65, v114, v65
	v_add_f32_e32 v114, v88, v72
	v_exp_f32_e32 v76, v76
	v_exp_f32_e32 v92, v92
	v_add_f32_e32 v65, v114, v65
	v_add_f32_e32 v114, v89, v73
	v_exp_f32_e32 v77, v77
	v_exp_f32_e32 v93, v93
	v_add_f32_e32 v65, v114, v65
	v_add_f32_e32 v114, v90, v74
	v_exp_f32_e32 v78, v78
	v_exp_f32_e32 v94, v94
	v_add_f32_e32 v65, v114, v65
	v_add_f32_e32 v114, v91, v75
	v_exp_f32_e32 v79, v79
	v_exp_f32_e32 v95, v95
	v_add_f32_e32 v65, v114, v65
	v_add_f32_e32 v114, v92, v76
	v_add_f32_e32 v65, v114, v65
	v_add_f32_e32 v114, v93, v77
	v_add_f32_e32 v65, v114, v65
	v_add_f32_e32 v114, v94, v78
	v_add_f32_e32 v65, v114, v65
	v_add_f32_e32 v114, v95, v79
	v_add_f32_e32 v65, v114, v65
	v_add_f32_e32 v65, v148, v65
	v_cvt_pk_bf16_f32 v134, v64, v113
	v_cvt_pk_bf16_f32 v135, v66, v67
	v_cvt_pk_bf16_f32 v136, v68, v69
	v_cvt_pk_bf16_f32 v137, v70, v71
	v_cvt_pk_bf16_f32 v120, v80, v81
	v_cvt_pk_bf16_f32 v121, v82, v83
	v_cvt_pk_bf16_f32 v122, v84, v85
	v_cvt_pk_bf16_f32 v123, v86, v87
	v_cvt_pk_bf16_f32 v130, v72, v73
	v_cvt_pk_bf16_f32 v131, v74, v75
	v_cvt_pk_bf16_f32 v132, v76, v77
	v_cvt_pk_bf16_f32 v133, v78, v79
	v_cvt_pk_bf16_f32 v112, v88, v89
	v_cvt_pk_bf16_f32 v113, v90, v91
	v_cvt_pk_bf16_f32 v114, v92, v93
	v_cvt_pk_bf16_f32 v115, v94, v95
.Lag_join:
	s_add_i32 s25, s25, 1
	s_cmp_lg_u32 s25, 37
	s_barrier
	s_cbranch_scc0 .LBB0_1161
	s_mov_b32 s84, s66
	s_mov_b32 s66, s71
	v_mov_b32_e32 v148, v65
	s_branch .LBB0_1153

.LBB0_1171:
	s_mul_i32 s68, s85, 0x9000
	v_add_u32_e32 v193, s68, v191
	s_mov_b32 s72, s70
	s_mul_i32 s68, s72, 0x9000
	s_mov_b32 s70, s85
	v_add_u32_e32 v221, s68, v192
	v_add_u32_e32 v222, 0x4000, v221
	v_add_u32_e32 v223, 0x5000, v221
	v_add_u32_e32 v227, 0x6800, v221
	v_add_u32_e32 v232, 0x7800, v221
	ds_read_b128 v[194:197], v193
	ds_read_b128 v[198:201], v193 offset:8704
	ds_read_b128 v[202:205], v193 offset:32
	ds_read_b128 v[206:209], v193 offset:8736
	ds_read_b128 v[210:213], v193 offset:64
	ds_read_b128 v[214:217], v193 offset:8768
	ds_read_b128 v[238:241], v193 offset:96
	s_waitcnt lgkmcnt(6)
	v_mfma_f32_32x32x16_bf16 v[80:95], v[194:197], v[112:115], v[64:79]
	ds_read_b128 v[194:197], v193 offset:8800
	s_mul_i32 s73, s71, 0x9000
	s_add_i32 s73, s73, 0
	v_add_u32_e32 v249, s73, v188
	v_add3_u32 v250, s73, v184, v185
	v_add_u32_e32 v251, v249, v190
	v_add_u32_e32 v249, v249, v189
	v_add3_u32 v218, s73, v186, v187
	s_waitcnt lgkmcnt(6)
	v_mfma_f32_32x32x16_bf16 v[96:111], v[198:201], v[112:115], v[64:79]
	ds_read2_b64 v[198:201], v222 offset0:128 offset1:130
	s_waitcnt vmcnt(0)
	ds_write_b128 v250, v[130:133]
	ds_write_b128 v218, v[134:137]
	ds_write_b128 v249, v[138:141] offset:17408
	ds_write_b128 v251, v[142:145] offset:17408
	s_waitcnt lgkmcnt(10)
	v_mfma_f32_32x32x16_bf16 v[80:95], v[202:205], v[116:119], v[80:95]
	ds_read2_b64 v[202:205], v223 offset0:192 offset1:194
	s_waitcnt lgkmcnt(10)
	v_mfma_f32_32x32x16_bf16 v[96:111], v[206:209], v[116:119], v[96:111]
	ds_read2_b64 v[206:209], v227 offset0:0 offset1:2
	s_waitcnt lgkmcnt(10)
	v_mfma_f32_32x32x16_bf16 v[80:95], v[210:213], v[120:123], v[80:95]
	ds_read2_b64 v[210:213], v232 offset0:64 offset1:66
	s_waitcnt lgkmcnt(10)
	v_mfma_f32_32x32x16_bf16 v[96:111], v[214:217], v[120:123], v[96:111]
	ds_read2_b64 v[214:217], v222 offset0:132 offset1:134
	s_waitcnt lgkmcnt(10)
	v_mfma_f32_32x32x16_bf16 v[80:95], v[238:241], v[124:127], v[80:95]
	ds_read2_b64 v[238:241], v223 offset0:196 offset1:198
	s_waitcnt lgkmcnt(10)
	v_mfma_f32_32x32x16_bf16 v[96:111], v[194:197], v[124:127], v[96:111]
	ds_read2_b64 v[194:197], v227 offset0:4 offset1:6
	s_waitcnt lgkmcnt(10)
	v_mfma_f32_32x32x16_bf16 v[48:63], v[198:201], v[158:161], v[48:63]
	ds_read2_b64 v[198:201], v232 offset0:68 offset1:70
	s_waitcnt lgkmcnt(6)
	v_mfma_f32_32x32x16_bf16 v[32:47], v[202:205], v[158:161], v[32:47]
	ds_read2_b64 v[202:205], v222 offset0:136 offset1:138
	s_add_i32 s68, s63, -2
	s_cmp_gt_u32 s68, 33
	s_cbranch_scc1 .Lad_nogl
	s_cmp_lt_u32 s68, 30
	s_cselect_b64 s[74:75], -1, 0
	s_and_b64 s[76:77], s[74:75], exec
	s_cselect_b32 s68, 0, 0xffffffe0
	s_add_i32 s68, s68, s63
	s_and_b64 s[76:77], s[74:75], exec
	s_cselect_b32 s73, s23, s65
	s_cselect_b32 s78, s22, s64
	s_lshl_b64 s[76:77], s[68:69], 16
	s_add_u32 s76, s78, s76
	s_addc_u32 s77, s73, s77
	s_and_b64 s[78:79], s[74:75], exec
	s_cselect_b32 s73, s25, s84
	s_cselect_b32 s80, s24, s66
	s_lshl_b32 s68, s68, 6
	s_lshl_b64 s[78:79], s[68:69], 1
	s_add_u32 s78, s80, s78
	s_addc_u32 s79, s73, s79
	s_and_b64 s[74:75], s[74:75], exec
	s_cselect_b32 s68, 11, 8
	v_lshl_add_u64 v[130:131], v[168:169], 1, s[76:77]
	v_lshl_add_u64 v[132:133], v[172:173], 1, s[76:77]
	v_lshl_add_u64 v[138:139], s[78:79], 0, v[128:129]
	v_lshlrev_b64 v[140:141], s68, v[176:177]
	v_lshlrev_b64 v[142:143], s68, v[178:179]
	v_lshl_add_u64 v[130:131], v[170:171], 1, v[130:131]
	v_lshl_add_u64 v[134:135], v[174:175], 1, v[132:133]
	v_lshl_add_u64 v[140:141], v[140:141], 1, v[138:139]
	v_lshl_add_u64 v[142:143], v[142:143], 1, v[138:139]
	global_load_dwordx4 v[130:133], v[130:131], off
	s_nop 0
	global_load_dwordx4 v[134:137], v[134:135], off
	s_nop 0
	global_load_dwordx4 v[138:141], v[140:141], off
	s_nop 0
	global_load_dwordx4 v[142:145], v[142:143], off
.Lad_nogl:
	s_waitcnt lgkmcnt(6)
	v_mfma_f32_32x32x16_bf16 v[16:31], v[206:209], v[158:161], v[16:31]
	ds_read2_b64 v[206:209], v223 offset0:200 offset1:202
	s_waitcnt lgkmcnt(6)
	v_mfma_f32_32x32x16_bf16 v[0:15], v[210:213], v[158:161], v[0:15]
	ds_read2_b64 v[210:213], v227 offset0:8 offset1:10
	s_waitcnt lgkmcnt(6)
	v_mfma_f32_32x32x16_bf16 v[48:63], v[214:217], v[154:157], v[48:63]
	ds_read2_b64 v[214:217], v232 offset0:72 offset1:74
	v_max3_f32 v233, v80, v96, v84
	v_max3_f32 v234, v81, v97, v85
	v_max3_f32 v242, v82, v98, v86
	v_max3_f32 v243, v83, v99, v87
	v_max3_f32 v233, v233, v100, v88
	v_max3_f32 v234, v234, v101, v89
	s_waitcnt lgkmcnt(6)
	v_mfma_f32_32x32x16_bf16 v[32:47], v[238:241], v[154:157], v[32:47]
	ds_read2_b64 v[238:241], v222 offset0:140 offset1:142
	v_max3_f32 v242, v242, v102, v90
	v_max3_f32 v243, v243, v103, v91
	v_max3_f32 v233, v233, v104, v92
	v_max3_f32 v234, v234, v105, v93
	v_max3_f32 v242, v242, v106, v94
	v_max3_f32 v243, v243, v107, v95
	s_waitcnt lgkmcnt(6)
	v_mfma_f32_32x32x16_bf16 v[16:31], v[194:197], v[154:157], v[16:31]
	ds_read2_b64 v[194:197], v223 offset0:204 offset1:206
	v_max_f32_e32 v233, v233, v108
	v_max_f32_e32 v234, v234, v109
	v_max_f32_e32 v242, v242, v110
	v_max_f32_e32 v243, v243, v111
	v_max3_f32 v233, v233, v234, v242
	v_max_f32_e32 v233, v233, v243
	s_waitcnt lgkmcnt(6)
	v_mfma_f32_32x32x16_bf16 v[0:15], v[198:201], v[154:157], v[0:15]
	ds_read2_b64 v[198:201], v227 offset0:12 offset1:14
	v_mov_b32_e32 v246, v233
	v_mov_b32_e32 v247, v233
	s_nop 1
	v_permlane32_swap_b32_e32 v246, v247
	v_max_f32_e32 v233, v246, v247
	v_cmp_lt_f32_e32 vcc, 0x41000000, v233
	s_cbranch_vccz .Lad_common
	s_waitcnt lgkmcnt(6)
	v_mfma_f32_32x32x16_bf16 v[48:63], v[202:205], v[150:153], v[48:63]
	ds_read2_b64 v[202:205], v232 offset0:76 offset1:78
	s_waitcnt lgkmcnt(6)
	v_mfma_f32_32x32x16_bf16 v[32:47], v[206:209], v[150:153], v[32:47]
	s_waitcnt lgkmcnt(5)
	v_mfma_f32_32x32x16_bf16 v[16:31], v[210:213], v[150:153], v[16:31]
	s_waitcnt lgkmcnt(4)
	v_mfma_f32_32x32x16_bf16 v[0:15], v[214:217], v[150:153], v[0:15]
	s_waitcnt lgkmcnt(3)
	v_mfma_f32_32x32x16_bf16 v[48:63], v[238:241], v[146:149], v[48:63]
	s_waitcnt lgkmcnt(2)
	v_mfma_f32_32x32x16_bf16 v[32:47], v[194:197], v[146:149], v[32:47]
	s_waitcnt lgkmcnt(1)
	v_mfma_f32_32x32x16_bf16 v[16:31], v[198:201], v[146:149], v[16:31]
	s_waitcnt lgkmcnt(0)
	v_mfma_f32_32x32x16_bf16 v[0:15], v[202:205], v[146:149], v[0:15]
	s_nop 7
	s_nop 3
	v_max_f32_e32 v64, v233, v233
	v_max_f32_e32 v66, 0, v64
	v_exp_f32_e64 v146, -v66
	v_add_f32_e32 v181, v181, v66
	v_xor_b32_e32 v64, 0x80000000, v181
	v_pk_add_f32 v[80:81], v[80:81], v[66:67] op_sel_hi:[1,0] neg_lo:[0,1] neg_hi:[0,1]
	v_pk_add_f32 v[96:97], v[96:97], v[66:67] op_sel_hi:[1,0] neg_lo:[0,1] neg_hi:[0,1]
	v_pk_add_f32 v[82:83], v[82:83], v[66:67] op_sel_hi:[1,0] neg_lo:[0,1] neg_hi:[0,1]
	v_pk_add_f32 v[98:99], v[98:99], v[66:67] op_sel_hi:[1,0] neg_lo:[0,1] neg_hi:[0,1]
	v_pk_add_f32 v[84:85], v[84:85], v[66:67] op_sel_hi:[1,0] neg_lo:[0,1] neg_hi:[0,1]
	v_pk_add_f32 v[100:101], v[100:101], v[66:67] op_sel_hi:[1,0] neg_lo:[0,1] neg_hi:[0,1]
	v_pk_add_f32 v[86:87], v[86:87], v[66:67] op_sel_hi:[1,0] neg_lo:[0,1] neg_hi:[0,1]
	v_pk_add_f32 v[102:103], v[102:103], v[66:67] op_sel_hi:[1,0] neg_lo:[0,1] neg_hi:[0,1]
	v_pk_add_f32 v[88:89], v[88:89], v[66:67] op_sel_hi:[1,0] neg_lo:[0,1] neg_hi:[0,1]
	v_pk_add_f32 v[104:105], v[104:105], v[66:67] op_sel_hi:[1,0] neg_lo:[0,1] neg_hi:[0,1]
	v_pk_add_f32 v[90:91], v[90:91], v[66:67] op_sel_hi:[1,0] neg_lo:[0,1] neg_hi:[0,1]
	v_pk_add_f32 v[106:107], v[106:107], v[66:67] op_sel_hi:[1,0] neg_lo:[0,1] neg_hi:[0,1]
	v_pk_add_f32 v[92:93], v[92:93], v[66:67] op_sel_hi:[1,0] neg_lo:[0,1] neg_hi:[0,1]
	v_pk_add_f32 v[108:109], v[108:109], v[66:67] op_sel_hi:[1,0] neg_lo:[0,1] neg_hi:[0,1]
	v_pk_add_f32 v[94:95], v[94:95], v[66:67] op_sel_hi:[1,0] neg_lo:[0,1] neg_hi:[0,1]
	v_pk_add_f32 v[110:111], v[110:111], v[66:67] op_sel_hi:[1,0] neg_lo:[0,1] neg_hi:[0,1]
	v_mov_b32_e32 v65, v64
	v_mov_b32_e32 v66, v64
	v_mov_b32_e32 v67, v64
	v_mov_b32_e32 v68, v64
	v_mov_b32_e32 v69, v64
	v_mov_b32_e32 v70, v64
	v_mov_b32_e32 v71, v64
	v_mov_b32_e32 v72, v64
	v_mov_b32_e32 v73, v64
	v_mov_b32_e32 v74, v64
	v_mov_b32_e32 v75, v64
	v_mov_b32_e32 v76, v64
	v_mov_b32_e32 v77, v64
	v_mov_b32_e32 v78, v64
	v_mov_b32_e32 v79, v64
	v_cmp_neq_f32_e32 vcc, 1.0, v146
	s_cbranch_vccz .Lad_rjoin
	v_pk_mul_f32 v[62:63], v[62:63], v[146:147] op_sel_hi:[1,0]
	v_pk_mul_f32 v[60:61], v[60:61], v[146:147] op_sel_hi:[1,0]
	v_pk_mul_f32 v[58:59], v[58:59], v[146:147] op_sel_hi:[1,0]
	v_pk_mul_f32 v[56:57], v[56:57], v[146:147] op_sel_hi:[1,0]
	v_pk_mul_f32 v[54:55], v[54:55], v[146:147] op_sel_hi:[1,0]
	v_pk_mul_f32 v[52:53], v[52:53], v[146:147] op_sel_hi:[1,0]
	v_pk_mul_f32 v[50:51], v[50:51], v[146:147] op_sel_hi:[1,0]
	v_pk_mul_f32 v[48:49], v[48:49], v[146:147] op_sel_hi:[1,0]
	v_pk_mul_f32 v[46:47], v[46:47], v[146:147] op_sel_hi:[1,0]
	v_pk_mul_f32 v[44:45], v[44:45], v[146:147] op_sel_hi:[1,0]
	v_pk_mul_f32 v[42:43], v[42:43], v[146:147] op_sel_hi:[1,0]
	v_pk_mul_f32 v[40:41], v[40:41], v[146:147] op_sel_hi:[1,0]
	v_pk_mul_f32 v[38:39], v[38:39], v[146:147] op_sel_hi:[1,0]
	v_pk_mul_f32 v[36:37], v[36:37], v[146:147] op_sel_hi:[1,0]
	v_pk_mul_f32 v[34:35], v[34:35], v[146:147] op_sel_hi:[1,0]
	v_pk_mul_f32 v[32:33], v[32:33], v[146:147] op_sel_hi:[1,0]
	v_pk_mul_f32 v[30:31], v[30:31], v[146:147] op_sel_hi:[1,0]
	v_pk_mul_f32 v[28:29], v[28:29], v[146:147] op_sel_hi:[1,0]
	v_pk_mul_f32 v[26:27], v[26:27], v[146:147] op_sel_hi:[1,0]
	v_pk_mul_f32 v[24:25], v[24:25], v[146:147] op_sel_hi:[1,0]
	v_pk_mul_f32 v[22:23], v[22:23], v[146:147] op_sel_hi:[1,0]
	v_pk_mul_f32 v[20:21], v[20:21], v[146:147] op_sel_hi:[1,0]
	v_pk_mul_f32 v[18:19], v[18:19], v[146:147] op_sel_hi:[1,0]
	v_pk_mul_f32 v[16:17], v[16:17], v[146:147] op_sel_hi:[1,0]
	v_pk_mul_f32 v[14:15], v[14:15], v[146:147] op_sel_hi:[1,0]
	v_pk_mul_f32 v[12:13], v[12:13], v[146:147] op_sel_hi:[1,0]
	v_pk_mul_f32 v[10:11], v[10:11], v[146:147] op_sel_hi:[1,0]
	v_pk_mul_f32 v[8:9], v[8:9], v[146:147] op_sel_hi:[1,0]
	v_pk_mul_f32 v[6:7], v[6:7], v[146:147] op_sel_hi:[1,0]
	v_pk_mul_f32 v[4:5], v[4:5], v[146:147] op_sel_hi:[1,0]
	v_pk_mul_f32 v[2:3], v[2:3], v[146:147] op_sel_hi:[1,0]
	v_pk_mul_f32 v[0:1], v[0:1], v[146:147] op_sel_hi:[1,0]
.Lad_rjoin:
	v_exp_f32_e32 v147, v80
	v_exp_f32_e32 v96, v96
	v_exp_f32_e32 v81, v81
	v_exp_f32_e32 v97, v97
	v_exp_f32_e32 v82, v82
	v_exp_f32_e32 v98, v98
	v_exp_f32_e32 v83, v83
	v_exp_f32_e32 v99, v99
	v_add_f32_e32 v80, v96, v147
	v_exp_f32_e32 v84, v84
	v_exp_f32_e32 v100, v100
	v_add_f32_e32 v80, 0, v80
	v_add_f32_e32 v148, v97, v81
	v_exp_f32_e32 v85, v85
	v_exp_f32_e32 v101, v101
	v_add_f32_e32 v80, v148, v80
	v_add_f32_e32 v148, v98, v82
	v_exp_f32_e32 v86, v86
	v_exp_f32_e32 v102, v102
	v_add_f32_e32 v80, v148, v80
	v_add_f32_e32 v148, v99, v83
	v_exp_f32_e32 v87, v87
	v_exp_f32_e32 v103, v103
	v_add_f32_e32 v80, v148, v80
	v_add_f32_e32 v148, v100, v84
	v_exp_f32_e32 v88, v88
	v_exp_f32_e32 v104, v104
	v_add_f32_e32 v80, v148, v80
	v_add_f32_e32 v148, v101, v85
	v_exp_f32_e32 v89, v89
	v_exp_f32_e32 v105, v105
	v_add_f32_e32 v80, v148, v80
	v_add_f32_e32 v148, v102, v86
	v_exp_f32_e32 v90, v90
	v_exp_f32_e32 v106, v106
	v_add_f32_e32 v80, v148, v80
	v_add_f32_e32 v148, v103, v87
	v_exp_f32_e32 v91, v91
	v_exp_f32_e32 v107, v107
	v_add_f32_e32 v80, v148, v80
	v_add_f32_e32 v148, v104, v88
	v_exp_f32_e32 v92, v92
	v_exp_f32_e32 v108, v108
	v_add_f32_e32 v80, v148, v80
	v_add_f32_e32 v148, v105, v89
	v_exp_f32_e32 v93, v93
	v_exp_f32_e32 v109, v109
	v_add_f32_e32 v80, v148, v80
	v_add_f32_e32 v148, v106, v90
	v_exp_f32_e32 v94, v94
	v_exp_f32_e32 v110, v110
	v_add_f32_e32 v80, v148, v80
	v_add_f32_e32 v148, v107, v91
	v_exp_f32_e32 v95, v95
	v_exp_f32_e32 v111, v111
	v_add_f32_e32 v80, v148, v80
	v_add_f32_e32 v148, v108, v92
	v_add_f32_e32 v80, v148, v80
	v_add_f32_e32 v148, v109, v93
	v_add_f32_e32 v80, v148, v80
	v_add_f32_e32 v148, v110, v94
	v_add_f32_e32 v80, v148, v80
	v_add_f32_e32 v148, v111, v95
	v_add_f32_e32 v80, v148, v80
	v_fmac_f32_e32 v80, v180, v146
	v_cvt_pk_bf16_f32 v158, v147, v81
	v_cvt_pk_bf16_f32 v159, v82, v83
	v_cvt_pk_bf16_f32 v160, v84, v85
	v_cvt_pk_bf16_f32 v161, v86, v87
	v_cvt_pk_bf16_f32 v150, v96, v97
	v_cvt_pk_bf16_f32 v151, v98, v99
	v_cvt_pk_bf16_f32 v152, v100, v101
	v_cvt_pk_bf16_f32 v153, v102, v103
	v_cvt_pk_bf16_f32 v154, v88, v89
	v_cvt_pk_bf16_f32 v155, v90, v91
	v_cvt_pk_bf16_f32 v156, v92, v93
	v_cvt_pk_bf16_f32 v157, v94, v95
	v_cvt_pk_bf16_f32 v146, v104, v105
	v_cvt_pk_bf16_f32 v147, v106, v107
	v_cvt_pk_bf16_f32 v148, v108, v109
	v_cvt_pk_bf16_f32 v149, v110, v111
	s_branch .Lad_join
.Lad_common:
	s_waitcnt lgkmcnt(6)
	v_mfma_f32_32x32x16_bf16 v[48:63], v[202:205], v[150:153], v[48:63]
	ds_read2_b64 v[202:205], v232 offset0:76 offset1:78
	v_exp_f32_e32 v219, v80
	v_exp_f32_e32 v96, v96
	v_exp_f32_e32 v81, v81
	v_exp_f32_e32 v97, v97
	v_exp_f32_e32 v82, v82
	v_exp_f32_e32 v98, v98
	v_exp_f32_e32 v83, v83
	v_exp_f32_e32 v99, v99
	s_waitcnt lgkmcnt(6)
	v_mfma_f32_32x32x16_bf16 v[32:47], v[206:209], v[150:153], v[32:47]
	v_add_f32_e32 v80, v96, v219
	v_exp_f32_e32 v84, v84
	v_exp_f32_e32 v100, v100
	v_add_f32_e32 v80, 0, v80
	v_add_f32_e32 v251, v97, v81
	v_exp_f32_e32 v85, v85
	v_exp_f32_e32 v101, v101
	v_add_f32_e32 v80, v251, v80
	s_waitcnt lgkmcnt(5)
	v_mfma_f32_32x32x16_bf16 v[16:31], v[210:213], v[150:153], v[16:31]
	v_add_f32_e32 v251, v98, v82
	v_exp_f32_e32 v86, v86
	v_exp_f32_e32 v102, v102
	v_add_f32_e32 v80, v251, v80
	v_add_f32_e32 v251, v99, v83
	v_exp_f32_e32 v87, v87
	v_exp_f32_e32 v103, v103
	v_add_f32_e32 v80, v251, v80
	s_waitcnt lgkmcnt(4)
	v_mfma_f32_32x32x16_bf16 v[0:15], v[214:217], v[150:153], v[0:15]
	v_add_f32_e32 v251, v100, v84
	v_exp_f32_e32 v88, v88
	v_exp_f32_e32 v104, v104
	v_add_f32_e32 v80, v251, v80
	v_add_f32_e32 v251, v101, v85
	v_exp_f32_e32 v89, v89
	v_exp_f32_e32 v105, v105
	v_add_f32_e32 v80, v251, v80
	s_waitcnt lgkmcnt(3)
	v_mfma_f32_32x32x16_bf16 v[48:63], v[238:241], v[146:149], v[48:63]
	v_add_f32_e32 v251, v102, v86
	v_exp_f32_e32 v90, v90
	v_exp_f32_e32 v106, v106
	v_add_f32_e32 v80, v251, v80
	v_add_f32_e32 v251, v103, v87
	v_exp_f32_e32 v91, v91
	v_exp_f32_e32 v107, v107
	v_add_f32_e32 v80, v251, v80
	s_waitcnt lgkmcnt(2)
	v_mfma_f32_32x32x16_bf16 v[32:47], v[194:197], v[146:149], v[32:47]
	v_add_f32_e32 v251, v104, v88
	v_exp_f32_e32 v92, v92
	v_exp_f32_e32 v108, v108
	v_add_f32_e32 v80, v251, v80
	v_add_f32_e32 v251, v105, v89
	v_exp_f32_e32 v93, v93
	v_exp_f32_e32 v109, v109
	v_add_f32_e32 v80, v251, v80
	s_waitcnt lgkmcnt(1)
	v_mfma_f32_32x32x16_bf16 v[16:31], v[198:201], v[146:149], v[16:31]
	v_add_f32_e32 v251, v106, v90
	v_exp_f32_e32 v94, v94
	v_exp_f32_e32 v110, v110
	v_add_f32_e32 v80, v251, v80
	v_add_f32_e32 v251, v107, v91
	v_exp_f32_e32 v95, v95
	v_exp_f32_e32 v111, v111
	v_add_f32_e32 v80, v251, v80
	s_waitcnt lgkmcnt(0)
	v_mfma_f32_32x32x16_bf16 v[0:15], v[202:205], v[146:149], v[0:15]
	v_add_f32_e32 v251, v108, v92
	v_add_f32_e32 v80, v251, v80
	v_add_f32_e32 v251, v109, v93
	v_add_f32_e32 v80, v251, v80
	v_add_f32_e32 v251, v110, v94
	v_add_f32_e32 v80, v251, v80
	v_add_f32_e32 v251, v111, v95
	v_add_f32_e32 v80, v251, v80
	v_add_f32_e32 v80, v180, v80
	v_cvt_pk_bf16_f32 v158, v219, v81
	v_cvt_pk_bf16_f32 v159, v82, v83
	v_cvt_pk_bf16_f32 v160, v84, v85
	v_cvt_pk_bf16_f32 v161, v86, v87
	v_cvt_pk_bf16_f32 v150, v96, v97
	v_cvt_pk_bf16_f32 v151, v98, v99
	v_cvt_pk_bf16_f32 v152, v100, v101
	v_cvt_pk_bf16_f32 v153, v102, v103
	v_cvt_pk_bf16_f32 v154, v88, v89
	v_cvt_pk_bf16_f32 v155, v90, v91
	v_cvt_pk_bf16_f32 v156, v92, v93
	v_cvt_pk_bf16_f32 v157, v94, v95
	v_cvt_pk_bf16_f32 v146, v104, v105
	v_cvt_pk_bf16_f32 v147, v106, v107
	v_cvt_pk_bf16_f32 v148, v108, v109
	v_cvt_pk_bf16_f32 v149, v110, v111
.Lad_join:
	s_add_i32 s63, s63, 1
	s_cmp_eq_u32 s63, 38
	s_barrier
	s_cbranch_scc1 .LBB0_1181
	s_mov_b32 s85, s71
	s_mov_b32 s71, s72
	v_mov_b32_e32 v180, v80
	s_branch .LBB0_1171

.LBB0_1299:
	s_ashr_i32 s29, s48, 5
	s_cmp_lg_u32 s29, 2
	s_cselect_b64 s[50:51], -1, 0
	s_lshl_b32 s30, s48, 8
	s_and_b32 s30, s30, 0x1f00
	v_mov_b32_e32 v128, v214
	v_mov_b32_e32 v130, v215
	s_add_i32 s30, s30, s63
	s_lshl_b32 s54, s29, 10
	v_add_u32_e32 v132, s30, v128
	s_lshl_b32 s30, s49, 8
	s_and_b32 s30, s30, 0x300
	v_mad_i64_i32 v[136:137], s[34:35], v132, s10, 0
	s_or_b32 s30, s30, s64
	s_ashr_i32 s55, s54, 31
	v_readlane_b32 s34, v253, 35
	s_cmp_gt_u32 s48, 31
	v_readlane_b32 s35, v253, 36
	v_lshl_add_u32 v130, v130, 3, s30
	s_cselect_b64 s[30:31], -1, 0
	v_cndmask_b32_e64 v128, 0, 1, s[34:35]
	v_ashrrev_i32_e32 v133, 31, v132
	v_cmp_ne_u32_e64 s[46:47], 1, v128
	v_cndmask_b32_e64 v128, 0, 1, s[30:31]
	v_lshlrev_b64 v[134:135], 10, v[132:133]
	s_andn2_b64 vcc, exec, s[34:35]
	v_ashrrev_i32_e32 v131, 31, v130
	v_cmp_ne_u32_e64 s[44:45], 1, v128
	v_readlane_b32 s36, v253, 37
	v_readlane_b32 s37, v253, 38
	s_nop 1
	s_and_b64 s[36:37], s[34:35], s[36:37]
	s_cbranch_scc1 .Lpc1_old
	s_and_b64 s[36:37], s[34:35], exec
	s_cbranch_scc0 .Lpc1_bj1
	s_and_b64 s[36:37], s[30:31], exec
	s_cbranch_scc1 .Lpc1_fast_b0t
.Lpc1_fast_b0n:
	v_lshlrev_b64 v[206:207], 1, v[130:131]
	v_lshl_add_u64 v[208:209], s[24:25], 0, v[136:137]
	v_lshl_add_u64 v[208:209], s[54:55], 1, v[208:209]
	v_lshl_add_u64 v[208:209], v[208:209], 0, v[206:207]
	s_and_b64 s[36:37], s[50:51], exec
	s_cselect_b32 s46, s22, s26
	s_cselect_b32 s47, s23, s27
	v_lshl_add_u64 v[212:213], v[134:135], 1, s[46:47]
	v_lshl_add_u64 v[212:213], v[212:213], 0, v[206:207]
	s_mov_b64 s[30:31], 0x18000
	s_mov_b64 s[34:35], 0x78000
	s_mov_b64 s[36:37], 0x8000
	s_mov_b64 s[44:45], 0x28000
	global_load_dwordx4 v[138:141], v[208:209], off
	v_lshl_add_u64 v[208:209], v[208:209], 0, s[30:31]
	global_load_dwordx4 v[142:145], v[208:209], off
	v_lshl_add_u64 v[208:209], v[208:209], 0, s[30:31]
	global_load_dwordx4 v[146:149], v[208:209], off
	v_lshl_add_u64 v[208:209], v[208:209], 0, s[30:31]
	global_load_dwordx4 v[150:153], v[208:209], off
	v_lshl_add_u64 v[208:209], v[208:209], 0, s[34:35]
	global_load_dwordx4 v[154:157], v[208:209], off
	v_lshl_add_u64 v[208:209], v[208:209], 0, s[30:31]
	global_load_dwordx4 v[158:161], v[208:209], off
	v_lshl_add_u64 v[208:209], v[208:209], 0, s[30:31]
	global_load_dwordx4 v[162:165], v[208:209], off
	v_lshl_add_u64 v[208:209], v[208:209], 0, s[30:31]
	global_load_dwordx4 v[166:169], v[208:209], off
	s_waitcnt vmcnt(7)
	v_lshlrev_b32_e32 v218, 16, v138
	v_and_b32_e32 v138, 0xffff0000, v138
	v_mul_f32_e32 v124, v124, v218
	v_mul_f32_e32 v125, v125, v138
	v_lshlrev_b32_e32 v218, 16, v139
	v_and_b32_e32 v139, 0xffff0000, v139
	v_mul_f32_e32 v126, v126, v218
	v_mul_f32_e32 v127, v127, v139
	v_lshlrev_b32_e32 v218, 16, v140
	v_and_b32_e32 v140, 0xffff0000, v140
	v_mul_f32_e32 v120, v120, v218
	v_mul_f32_e32 v121, v121, v140
	v_lshlrev_b32_e32 v218, 16, v141
	v_and_b32_e32 v141, 0xffff0000, v141
	v_mul_f32_e32 v122, v122, v218
	v_mul_f32_e32 v123, v123, v141
	v_cvt_pk_bf16_f32 v138, v124, v125
	v_cvt_pk_bf16_f32 v139, v126, v127
	v_cvt_pk_bf16_f32 v140, v120, v121
	v_cvt_pk_bf16_f32 v141, v122, v123
	global_store_dwordx4 v[212:213], v[138:141], off
	s_nop 0
	v_lshl_add_u64 v[212:213], v[212:213], 0, s[36:37]
	s_waitcnt vmcnt(7)
	v_lshlrev_b32_e32 v218, 16, v142
	v_and_b32_e32 v142, 0xffff0000, v142
	v_mul_f32_e32 v108, v108, v218
	v_mul_f32_e32 v109, v109, v142
	v_lshlrev_b32_e32 v218, 16, v143
	v_and_b32_e32 v143, 0xffff0000, v143
	v_mul_f32_e32 v110, v110, v218
	v_mul_f32_e32 v111, v111, v143
	v_lshlrev_b32_e32 v218, 16, v144
	v_and_b32_e32 v144, 0xffff0000, v144
	v_mul_f32_e32 v104, v104, v218
	v_mul_f32_e32 v105, v105, v144
	v_lshlrev_b32_e32 v218, 16, v145
	v_and_b32_e32 v145, 0xffff0000, v145
	v_mul_f32_e32 v106, v106, v218
	v_mul_f32_e32 v107, v107, v145
	v_cvt_pk_bf16_f32 v142, v108, v109
	v_cvt_pk_bf16_f32 v143, v110, v111
	v_cvt_pk_bf16_f32 v144, v104, v105
	v_cvt_pk_bf16_f32 v145, v106, v107
	global_store_dwordx4 v[212:213], v[142:145], off
	s_nop 0
	v_lshl_add_u64 v[212:213], v[212:213], 0, s[36:37]
	s_waitcnt vmcnt(7)
	v_lshlrev_b32_e32 v218, 16, v146
	v_and_b32_e32 v146, 0xffff0000, v146
	v_mul_f32_e32 v92, v92, v218
	v_mul_f32_e32 v93, v93, v146
	v_lshlrev_b32_e32 v218, 16, v147
	v_and_b32_e32 v147, 0xffff0000, v147
	v_mul_f32_e32 v94, v94, v218
	v_mul_f32_e32 v95, v95, v147
	v_lshlrev_b32_e32 v218, 16, v148
	v_and_b32_e32 v148, 0xffff0000, v148
	v_mul_f32_e32 v88, v88, v218
	v_mul_f32_e32 v89, v89, v148
	v_lshlrev_b32_e32 v218, 16, v149
	v_and_b32_e32 v149, 0xffff0000, v149
	v_mul_f32_e32 v90, v90, v218
	v_mul_f32_e32 v91, v91, v149
	v_cvt_pk_bf16_f32 v146, v92, v93
	v_cvt_pk_bf16_f32 v147, v94, v95
	v_cvt_pk_bf16_f32 v148, v88, v89
	v_cvt_pk_bf16_f32 v149, v90, v91
	global_store_dwordx4 v[212:213], v[146:149], off
	s_nop 0
	v_lshl_add_u64 v[212:213], v[212:213], 0, s[36:37]
	s_waitcnt vmcnt(7)
	v_lshlrev_b32_e32 v218, 16, v150
	v_and_b32_e32 v150, 0xffff0000, v150
	v_mul_f32_e32 v76, v76, v218
	v_mul_f32_e32 v77, v77, v150
	v_lshlrev_b32_e32 v218, 16, v151
	v_and_b32_e32 v151, 0xffff0000, v151
	v_mul_f32_e32 v78, v78, v218
	v_mul_f32_e32 v79, v79, v151
	v_lshlrev_b32_e32 v218, 16, v152
	v_and_b32_e32 v152, 0xffff0000, v152
	v_mul_f32_e32 v72, v72, v218
	v_mul_f32_e32 v73, v73, v152
	v_lshlrev_b32_e32 v218, 16, v153
	v_and_b32_e32 v153, 0xffff0000, v153
	v_mul_f32_e32 v74, v74, v218
	v_mul_f32_e32 v75, v75, v153
	v_cvt_pk_bf16_f32 v150, v76, v77
	v_cvt_pk_bf16_f32 v151, v78, v79
	v_cvt_pk_bf16_f32 v152, v72, v73
	v_cvt_pk_bf16_f32 v153, v74, v75
	global_store_dwordx4 v[212:213], v[150:153], off
	s_nop 0
	v_lshl_add_u64 v[212:213], v[212:213], 0, s[44:45]
	s_waitcnt vmcnt(7)
	v_lshlrev_b32_e32 v218, 16, v154
	v_and_b32_e32 v154, 0xffff0000, v154
	v_mul_f32_e32 v60, v60, v218
	v_mul_f32_e32 v61, v61, v154
	v_lshlrev_b32_e32 v218, 16, v155
	v_and_b32_e32 v155, 0xffff0000, v155
	v_mul_f32_e32 v62, v62, v218
	v_mul_f32_e32 v63, v63, v155
	v_lshlrev_b32_e32 v218, 16, v156
	v_and_b32_e32 v156, 0xffff0000, v156
	v_mul_f32_e32 v56, v56, v218
	v_mul_f32_e32 v57, v57, v156
	v_lshlrev_b32_e32 v218, 16, v157
	v_and_b32_e32 v157, 0xffff0000, v157
	v_mul_f32_e32 v58, v58, v218
	v_mul_f32_e32 v59, v59, v157
	v_cvt_pk_bf16_f32 v154, v60, v61
	v_cvt_pk_bf16_f32 v155, v62, v63
	v_cvt_pk_bf16_f32 v156, v56, v57
	v_cvt_pk_bf16_f32 v157, v58, v59
	global_store_dwordx4 v[212:213], v[154:157], off
	s_nop 0
	v_lshl_add_u64 v[212:213], v[212:213], 0, s[36:37]
	s_waitcnt vmcnt(7)
	v_lshlrev_b32_e32 v218, 16, v158
	v_and_b32_e32 v158, 0xffff0000, v158
	v_mul_f32_e32 v44, v44, v218
	v_mul_f32_e32 v45, v45, v158
	v_lshlrev_b32_e32 v218, 16, v159
	v_and_b32_e32 v159, 0xffff0000, v159
	v_mul_f32_e32 v46, v46, v218
	v_mul_f32_e32 v47, v47, v159
	v_lshlrev_b32_e32 v218, 16, v160
	v_and_b32_e32 v160, 0xffff0000, v160
	v_mul_f32_e32 v40, v40, v218
	v_mul_f32_e32 v41, v41, v160
	v_lshlrev_b32_e32 v218, 16, v161
	v_and_b32_e32 v161, 0xffff0000, v161
	v_mul_f32_e32 v42, v42, v218
	v_mul_f32_e32 v43, v43, v161
	v_cvt_pk_bf16_f32 v158, v44, v45
	v_cvt_pk_bf16_f32 v159, v46, v47
	v_cvt_pk_bf16_f32 v160, v40, v41
	v_cvt_pk_bf16_f32 v161, v42, v43
	global_store_dwordx4 v[212:213], v[158:161], off
	s_nop 0
	v_lshl_add_u64 v[212:213], v[212:213], 0, s[36:37]
	s_waitcnt vmcnt(7)
	v_lshlrev_b32_e32 v218, 16, v162
	v_and_b32_e32 v162, 0xffff0000, v162
	v_mul_f32_e32 v28, v28, v218
	v_mul_f32_e32 v29, v29, v162
	v_lshlrev_b32_e32 v218, 16, v163
	v_and_b32_e32 v163, 0xffff0000, v163
	v_mul_f32_e32 v30, v30, v218
	v_mul_f32_e32 v31, v31, v163
	v_lshlrev_b32_e32 v218, 16, v164
	v_and_b32_e32 v164, 0xffff0000, v164
	v_mul_f32_e32 v24, v24, v218
	v_mul_f32_e32 v25, v25, v164
	v_lshlrev_b32_e32 v218, 16, v165
	v_and_b32_e32 v165, 0xffff0000, v165
	v_mul_f32_e32 v26, v26, v218
	v_mul_f32_e32 v27, v27, v165
	v_cvt_pk_bf16_f32 v162, v28, v29
	v_cvt_pk_bf16_f32 v163, v30, v31
	v_cvt_pk_bf16_f32 v164, v24, v25
	v_cvt_pk_bf16_f32 v165, v26, v27
	global_store_dwordx4 v[212:213], v[162:165], off
	s_nop 0
	v_lshl_add_u64 v[212:213], v[212:213], 0, s[36:37]
	s_waitcnt vmcnt(7)
	v_lshlrev_b32_e32 v218, 16, v166
	v_and_b32_e32 v166, 0xffff0000, v166
	v_mul_f32_e32 v12, v12, v218
	v_mul_f32_e32 v13, v13, v166
	v_lshlrev_b32_e32 v218, 16, v167
	v_and_b32_e32 v167, 0xffff0000, v167
	v_mul_f32_e32 v14, v14, v218
	v_mul_f32_e32 v15, v15, v167
	v_lshlrev_b32_e32 v218, 16, v168
	v_and_b32_e32 v168, 0xffff0000, v168
	v_mul_f32_e32 v8, v8, v218
	v_mul_f32_e32 v9, v9, v168
	v_lshlrev_b32_e32 v218, 16, v169
	v_and_b32_e32 v169, 0xffff0000, v169
	v_mul_f32_e32 v10, v10, v218
	v_mul_f32_e32 v11, v11, v169
	v_cvt_pk_bf16_f32 v166, v12, v13
	v_cvt_pk_bf16_f32 v167, v14, v15
	v_cvt_pk_bf16_f32 v168, v8, v9
	v_cvt_pk_bf16_f32 v169, v10, v11
	global_store_dwordx4 v[212:213], v[166:169], off
	s_branch .LBB0_1411
.Lpc1_fast_b0t:
	v_lshlrev_b64 v[206:207], 1, v[130:131]
	v_lshl_add_u64 v[208:209], s[24:25], 0, v[136:137]
	v_lshl_add_u64 v[208:209], s[54:55], 1, v[208:209]
	v_lshl_add_u64 v[208:209], v[208:209], 0, v[206:207]
	v_lshl_add_u64 v[210:211], v[134:135], 1, s[22:23]
	v_lshl_add_u64 v[210:211], v[210:211], 0, v[206:207]
	s_and_b64 s[36:37], s[50:51], exec
	s_cselect_b32 s46, s22, s26
	s_cselect_b32 s47, s23, s27
	v_lshl_add_u64 v[212:213], v[134:135], 1, s[46:47]
	v_lshl_add_u64 v[212:213], v[212:213], 0, v[206:207]
	s_mov_b64 s[30:31], 0x18000
	s_mov_b64 s[34:35], 0x78000
	s_mov_b64 s[36:37], 0x8000
	s_mov_b64 s[44:45], 0x28000
	global_load_dwordx4 v[138:141], v[208:209], off
	global_load_dwordx4 v[170:173], v[210:211], off
	v_lshl_add_u64 v[208:209], v[208:209], 0, s[30:31]
	v_lshl_add_u64 v[210:211], v[210:211], 0, s[36:37]
	global_load_dwordx4 v[142:145], v[208:209], off
	global_load_dwordx4 v[174:177], v[210:211], off
	v_lshl_add_u64 v[208:209], v[208:209], 0, s[30:31]
	v_lshl_add_u64 v[210:211], v[210:211], 0, s[36:37]
	global_load_dwordx4 v[146:149], v[208:209], off
	global_load_dwordx4 v[178:181], v[210:211], off
	v_lshl_add_u64 v[208:209], v[208:209], 0, s[30:31]
	v_lshl_add_u64 v[210:211], v[210:211], 0, s[36:37]
	global_load_dwordx4 v[150:153], v[208:209], off
	global_load_dwordx4 v[182:185], v[210:211], off
	v_lshl_add_u64 v[208:209], v[208:209], 0, s[34:35]
	v_lshl_add_u64 v[210:211], v[210:211], 0, s[44:45]
	global_load_dwordx4 v[154:157], v[208:209], off
	global_load_dwordx4 v[186:189], v[210:211], off
	v_lshl_add_u64 v[208:209], v[208:209], 0, s[30:31]
	v_lshl_add_u64 v[210:211], v[210:211], 0, s[36:37]
	global_load_dwordx4 v[158:161], v[208:209], off
	global_load_dwordx4 v[190:193], v[210:211], off
	v_lshl_add_u64 v[208:209], v[208:209], 0, s[30:31]
	v_lshl_add_u64 v[210:211], v[210:211], 0, s[36:37]
	global_load_dwordx4 v[162:165], v[208:209], off
	global_load_dwordx4 v[130:133], v[210:211], off
	v_lshl_add_u64 v[208:209], v[208:209], 0, s[30:31]
	v_lshl_add_u64 v[210:211], v[210:211], 0, s[36:37]
	global_load_dwordx4 v[166:169], v[208:209], off
	global_load_dwordx4 v[134:137], v[210:211], off
	s_waitcnt vmcnt(14)
	v_lshlrev_b32_e32 v218, 16, v138
	v_and_b32_e32 v138, 0xffff0000, v138
	v_mul_f32_e32 v124, v124, v218
	v_mul_f32_e32 v125, v125, v138
	v_lshlrev_b32_e32 v218, 16, v139
	v_and_b32_e32 v139, 0xffff0000, v139
	v_mul_f32_e32 v126, v126, v218
	v_mul_f32_e32 v127, v127, v139
	v_lshlrev_b32_e32 v218, 16, v140
	v_and_b32_e32 v140, 0xffff0000, v140
	v_mul_f32_e32 v120, v120, v218
	v_mul_f32_e32 v121, v121, v140
	v_lshlrev_b32_e32 v218, 16, v141
	v_and_b32_e32 v141, 0xffff0000, v141
	v_mul_f32_e32 v122, v122, v218
	v_mul_f32_e32 v123, v123, v141
	v_lshlrev_b32_e32 v219, 16, v170
	v_and_b32_e32 v170, 0xffff0000, v170
	v_add_f32_e32 v124, v124, v219
	v_add_f32_e32 v125, v125, v170
	v_lshlrev_b32_e32 v219, 16, v171
	v_and_b32_e32 v171, 0xffff0000, v171
	v_add_f32_e32 v126, v126, v219
	v_add_f32_e32 v127, v127, v171
	v_lshlrev_b32_e32 v219, 16, v172
	v_and_b32_e32 v172, 0xffff0000, v172
	v_add_f32_e32 v120, v120, v219
	v_add_f32_e32 v121, v121, v172
	v_lshlrev_b32_e32 v219, 16, v173
	v_and_b32_e32 v173, 0xffff0000, v173
	v_add_f32_e32 v122, v122, v219
	v_add_f32_e32 v123, v123, v173
	v_cvt_pk_bf16_f32 v138, v124, v125
	v_cvt_pk_bf16_f32 v139, v126, v127
	v_cvt_pk_bf16_f32 v140, v120, v121
	v_cvt_pk_bf16_f32 v141, v122, v123
	global_store_dwordx4 v[212:213], v[138:141], off
	s_nop 0
	v_lshl_add_u64 v[212:213], v[212:213], 0, s[36:37]
	s_waitcnt vmcnt(13)
	v_lshlrev_b32_e32 v218, 16, v142
	v_and_b32_e32 v142, 0xffff0000, v142
	v_mul_f32_e32 v108, v108, v218
	v_mul_f32_e32 v109, v109, v142
	v_lshlrev_b32_e32 v218, 16, v143
	v_and_b32_e32 v143, 0xffff0000, v143
	v_mul_f32_e32 v110, v110, v218
	v_mul_f32_e32 v111, v111, v143
	v_lshlrev_b32_e32 v218, 16, v144
	v_and_b32_e32 v144, 0xffff0000, v144
	v_mul_f32_e32 v104, v104, v218
	v_mul_f32_e32 v105, v105, v144
	v_lshlrev_b32_e32 v218, 16, v145
	v_and_b32_e32 v145, 0xffff0000, v145
	v_mul_f32_e32 v106, v106, v218
	v_mul_f32_e32 v107, v107, v145
	v_lshlrev_b32_e32 v219, 16, v174
	v_and_b32_e32 v174, 0xffff0000, v174
	v_add_f32_e32 v108, v108, v219
	v_add_f32_e32 v109, v109, v174
	v_lshlrev_b32_e32 v219, 16, v175
	v_and_b32_e32 v175, 0xffff0000, v175
	v_add_f32_e32 v110, v110, v219
	v_add_f32_e32 v111, v111, v175
	v_lshlrev_b32_e32 v219, 16, v176
	v_and_b32_e32 v176, 0xffff0000, v176
	v_add_f32_e32 v104, v104, v219
	v_add_f32_e32 v105, v105, v176
	v_lshlrev_b32_e32 v219, 16, v177
	v_and_b32_e32 v177, 0xffff0000, v177
	v_add_f32_e32 v106, v106, v219
	v_add_f32_e32 v107, v107, v177
	v_cvt_pk_bf16_f32 v142, v108, v109
	v_cvt_pk_bf16_f32 v143, v110, v111
	v_cvt_pk_bf16_f32 v144, v104, v105
	v_cvt_pk_bf16_f32 v145, v106, v107
	global_store_dwordx4 v[212:213], v[142:145], off
	s_nop 0
	v_lshl_add_u64 v[212:213], v[212:213], 0, s[36:37]
	s_waitcnt vmcnt(12)
	v_lshlrev_b32_e32 v218, 16, v146
	v_and_b32_e32 v146, 0xffff0000, v146
	v_mul_f32_e32 v92, v92, v218
	v_mul_f32_e32 v93, v93, v146
	v_lshlrev_b32_e32 v218, 16, v147
	v_and_b32_e32 v147, 0xffff0000, v147
	v_mul_f32_e32 v94, v94, v218
	v_mul_f32_e32 v95, v95, v147
	v_lshlrev_b32_e32 v218, 16, v148
	v_and_b32_e32 v148, 0xffff0000, v148
	v_mul_f32_e32 v88, v88, v218
	v_mul_f32_e32 v89, v89, v148
	v_lshlrev_b32_e32 v218, 16, v149
	v_and_b32_e32 v149, 0xffff0000, v149
	v_mul_f32_e32 v90, v90, v218
	v_mul_f32_e32 v91, v91, v149
	v_lshlrev_b32_e32 v219, 16, v178
	v_and_b32_e32 v178, 0xffff0000, v178
	v_add_f32_e32 v92, v92, v219
	v_add_f32_e32 v93, v93, v178
	v_lshlrev_b32_e32 v219, 16, v179
	v_and_b32_e32 v179, 0xffff0000, v179
	v_add_f32_e32 v94, v94, v219
	v_add_f32_e32 v95, v95, v179
	v_lshlrev_b32_e32 v219, 16, v180
	v_and_b32_e32 v180, 0xffff0000, v180
	v_add_f32_e32 v88, v88, v219
	v_add_f32_e32 v89, v89, v180
	v_lshlrev_b32_e32 v219, 16, v181
	v_and_b32_e32 v181, 0xffff0000, v181
	v_add_f32_e32 v90, v90, v219
	v_add_f32_e32 v91, v91, v181
	v_cvt_pk_bf16_f32 v146, v92, v93
	v_cvt_pk_bf16_f32 v147, v94, v95
	v_cvt_pk_bf16_f32 v148, v88, v89
	v_cvt_pk_bf16_f32 v149, v90, v91
	global_store_dwordx4 v[212:213], v[146:149], off
	s_nop 0
	v_lshl_add_u64 v[212:213], v[212:213], 0, s[36:37]
	s_waitcnt vmcnt(11)
	v_lshlrev_b32_e32 v218, 16, v150
	v_and_b32_e32 v150, 0xffff0000, v150
	v_mul_f32_e32 v76, v76, v218
	v_mul_f32_e32 v77, v77, v150
	v_lshlrev_b32_e32 v218, 16, v151
	v_and_b32_e32 v151, 0xffff0000, v151
	v_mul_f32_e32 v78, v78, v218
	v_mul_f32_e32 v79, v79, v151
	v_lshlrev_b32_e32 v218, 16, v152
	v_and_b32_e32 v152, 0xffff0000, v152
	v_mul_f32_e32 v72, v72, v218
	v_mul_f32_e32 v73, v73, v152
	v_lshlrev_b32_e32 v218, 16, v153
	v_and_b32_e32 v153, 0xffff0000, v153
	v_mul_f32_e32 v74, v74, v218
	v_mul_f32_e32 v75, v75, v153
	v_lshlrev_b32_e32 v219, 16, v182
	v_and_b32_e32 v182, 0xffff0000, v182
	v_add_f32_e32 v76, v76, v219
	v_add_f32_e32 v77, v77, v182
	v_lshlrev_b32_e32 v219, 16, v183
	v_and_b32_e32 v183, 0xffff0000, v183
	v_add_f32_e32 v78, v78, v219
	v_add_f32_e32 v79, v79, v183
	v_lshlrev_b32_e32 v219, 16, v184
	v_and_b32_e32 v184, 0xffff0000, v184
	v_add_f32_e32 v72, v72, v219
	v_add_f32_e32 v73, v73, v184
	v_lshlrev_b32_e32 v219, 16, v185
	v_and_b32_e32 v185, 0xffff0000, v185
	v_add_f32_e32 v74, v74, v219
	v_add_f32_e32 v75, v75, v185
	v_cvt_pk_bf16_f32 v150, v76, v77
	v_cvt_pk_bf16_f32 v151, v78, v79
	v_cvt_pk_bf16_f32 v152, v72, v73
	v_cvt_pk_bf16_f32 v153, v74, v75
	global_store_dwordx4 v[212:213], v[150:153], off
	s_nop 0
	v_lshl_add_u64 v[212:213], v[212:213], 0, s[44:45]
	s_waitcnt vmcnt(10)
	v_lshlrev_b32_e32 v218, 16, v154
	v_and_b32_e32 v154, 0xffff0000, v154
	v_mul_f32_e32 v60, v60, v218
	v_mul_f32_e32 v61, v61, v154
	v_lshlrev_b32_e32 v218, 16, v155
	v_and_b32_e32 v155, 0xffff0000, v155
	v_mul_f32_e32 v62, v62, v218
	v_mul_f32_e32 v63, v63, v155
	v_lshlrev_b32_e32 v218, 16, v156
	v_and_b32_e32 v156, 0xffff0000, v156
	v_mul_f32_e32 v56, v56, v218
	v_mul_f32_e32 v57, v57, v156
	v_lshlrev_b32_e32 v218, 16, v157
	v_and_b32_e32 v157, 0xffff0000, v157
	v_mul_f32_e32 v58, v58, v218
	v_mul_f32_e32 v59, v59, v157
	v_lshlrev_b32_e32 v219, 16, v186
	v_and_b32_e32 v186, 0xffff0000, v186
	v_add_f32_e32 v60, v60, v219
	v_add_f32_e32 v61, v61, v186
	v_lshlrev_b32_e32 v219, 16, v187
	v_and_b32_e32 v187, 0xffff0000, v187
	v_add_f32_e32 v62, v62, v219
	v_add_f32_e32 v63, v63, v187
	v_lshlrev_b32_e32 v219, 16, v188
	v_and_b32_e32 v188, 0xffff0000, v188
	v_add_f32_e32 v56, v56, v219
	v_add_f32_e32 v57, v57, v188
	v_lshlrev_b32_e32 v219, 16, v189
	v_and_b32_e32 v189, 0xffff0000, v189
	v_add_f32_e32 v58, v58, v219
	v_add_f32_e32 v59, v59, v189
	v_cvt_pk_bf16_f32 v154, v60, v61
	v_cvt_pk_bf16_f32 v155, v62, v63
	v_cvt_pk_bf16_f32 v156, v56, v57
	v_cvt_pk_bf16_f32 v157, v58, v59
	global_store_dwordx4 v[212:213], v[154:157], off
	s_nop 0
	v_lshl_add_u64 v[212:213], v[212:213], 0, s[36:37]
	s_waitcnt vmcnt(9)
	v_lshlrev_b32_e32 v218, 16, v158
	v_and_b32_e32 v158, 0xffff0000, v158
	v_mul_f32_e32 v44, v44, v218
	v_mul_f32_e32 v45, v45, v158
	v_lshlrev_b32_e32 v218, 16, v159
	v_and_b32_e32 v159, 0xffff0000, v159
	v_mul_f32_e32 v46, v46, v218
	v_mul_f32_e32 v47, v47, v159
	v_lshlrev_b32_e32 v218, 16, v160
	v_and_b32_e32 v160, 0xffff0000, v160
	v_mul_f32_e32 v40, v40, v218
	v_mul_f32_e32 v41, v41, v160
	v_lshlrev_b32_e32 v218, 16, v161
	v_and_b32_e32 v161, 0xffff0000, v161
	v_mul_f32_e32 v42, v42, v218
	v_mul_f32_e32 v43, v43, v161
	v_lshlrev_b32_e32 v219, 16, v190
	v_and_b32_e32 v190, 0xffff0000, v190
	v_add_f32_e32 v44, v44, v219
	v_add_f32_e32 v45, v45, v190
	v_lshlrev_b32_e32 v219, 16, v191
	v_and_b32_e32 v191, 0xffff0000, v191
	v_add_f32_e32 v46, v46, v219
	v_add_f32_e32 v47, v47, v191
	v_lshlrev_b32_e32 v219, 16, v192
	v_and_b32_e32 v192, 0xffff0000, v192
	v_add_f32_e32 v40, v40, v219
	v_add_f32_e32 v41, v41, v192
	v_lshlrev_b32_e32 v219, 16, v193
	v_and_b32_e32 v193, 0xffff0000, v193
	v_add_f32_e32 v42, v42, v219
	v_add_f32_e32 v43, v43, v193
	v_cvt_pk_bf16_f32 v158, v44, v45
	v_cvt_pk_bf16_f32 v159, v46, v47
	v_cvt_pk_bf16_f32 v160, v40, v41
	v_cvt_pk_bf16_f32 v161, v42, v43
	global_store_dwordx4 v[212:213], v[158:161], off
	s_nop 0
	v_lshl_add_u64 v[212:213], v[212:213], 0, s[36:37]
	s_waitcnt vmcnt(8)
	v_lshlrev_b32_e32 v218, 16, v162
	v_and_b32_e32 v162, 0xffff0000, v162
	v_mul_f32_e32 v28, v28, v218
	v_mul_f32_e32 v29, v29, v162
	v_lshlrev_b32_e32 v218, 16, v163
	v_and_b32_e32 v163, 0xffff0000, v163
	v_mul_f32_e32 v30, v30, v218
	v_mul_f32_e32 v31, v31, v163
	v_lshlrev_b32_e32 v218, 16, v164
	v_and_b32_e32 v164, 0xffff0000, v164
	v_mul_f32_e32 v24, v24, v218
	v_mul_f32_e32 v25, v25, v164
	v_lshlrev_b32_e32 v218, 16, v165
	v_and_b32_e32 v165, 0xffff0000, v165
	v_mul_f32_e32 v26, v26, v218
	v_mul_f32_e32 v27, v27, v165
	v_lshlrev_b32_e32 v219, 16, v130
	v_and_b32_e32 v130, 0xffff0000, v130
	v_add_f32_e32 v28, v28, v219
	v_add_f32_e32 v29, v29, v130
	v_lshlrev_b32_e32 v219, 16, v131
	v_and_b32_e32 v131, 0xffff0000, v131
	v_add_f32_e32 v30, v30, v219
	v_add_f32_e32 v31, v31, v131
	v_lshlrev_b32_e32 v219, 16, v132
	v_and_b32_e32 v132, 0xffff0000, v132
	v_add_f32_e32 v24, v24, v219
	v_add_f32_e32 v25, v25, v132
	v_lshlrev_b32_e32 v219, 16, v133
	v_and_b32_e32 v133, 0xffff0000, v133
	v_add_f32_e32 v26, v26, v219
	v_add_f32_e32 v27, v27, v133
	v_cvt_pk_bf16_f32 v162, v28, v29
	v_cvt_pk_bf16_f32 v163, v30, v31
	v_cvt_pk_bf16_f32 v164, v24, v25
	v_cvt_pk_bf16_f32 v165, v26, v27
	global_store_dwordx4 v[212:213], v[162:165], off
	s_nop 0
	v_lshl_add_u64 v[212:213], v[212:213], 0, s[36:37]
	s_waitcnt vmcnt(7)
	v_lshlrev_b32_e32 v218, 16, v166
	v_and_b32_e32 v166, 0xffff0000, v166
	v_mul_f32_e32 v12, v12, v218
	v_mul_f32_e32 v13, v13, v166
	v_lshlrev_b32_e32 v218, 16, v167
	v_and_b32_e32 v167, 0xffff0000, v167
	v_mul_f32_e32 v14, v14, v218
	v_mul_f32_e32 v15, v15, v167
	v_lshlrev_b32_e32 v218, 16, v168
	v_and_b32_e32 v168, 0xffff0000, v168
	v_mul_f32_e32 v8, v8, v218
	v_mul_f32_e32 v9, v9, v168
	v_lshlrev_b32_e32 v218, 16, v169
	v_and_b32_e32 v169, 0xffff0000, v169
	v_mul_f32_e32 v10, v10, v218
	v_mul_f32_e32 v11, v11, v169
	v_lshlrev_b32_e32 v219, 16, v134
	v_and_b32_e32 v134, 0xffff0000, v134
	v_add_f32_e32 v12, v12, v219
	v_add_f32_e32 v13, v13, v134
	v_lshlrev_b32_e32 v219, 16, v135
	v_and_b32_e32 v135, 0xffff0000, v135
	v_add_f32_e32 v14, v14, v219
	v_add_f32_e32 v15, v15, v135
	v_lshlrev_b32_e32 v219, 16, v136
	v_and_b32_e32 v136, 0xffff0000, v136
	v_add_f32_e32 v8, v8, v219
	v_add_f32_e32 v9, v9, v136
	v_lshlrev_b32_e32 v219, 16, v137
	v_and_b32_e32 v137, 0xffff0000, v137
	v_add_f32_e32 v10, v10, v219
	v_add_f32_e32 v11, v11, v137
	v_cvt_pk_bf16_f32 v166, v12, v13
	v_cvt_pk_bf16_f32 v167, v14, v15
	v_cvt_pk_bf16_f32 v168, v8, v9
	v_cvt_pk_bf16_f32 v169, v10, v11
	global_store_dwordx4 v[212:213], v[166:169], off
	s_branch .LBB0_1411
.Lpc1_bj1:
	s_and_b64 s[36:37], s[30:31], exec
	s_cbranch_scc1 .Lpc1_fast_b1t
.Lpc1_fast_b1n:
	v_lshlrev_b64 v[206:207], 1, v[130:131]
	v_lshl_add_u64 v[208:209], s[24:25], 0, v[136:137]
	v_lshl_add_u64 v[208:209], s[54:55], 1, v[208:209]
	v_lshl_add_u64 v[208:209], v[208:209], 0, v[206:207]
	s_and_b64 s[36:37], s[50:51], exec
	s_cselect_b32 s46, s22, s26
	s_cselect_b32 s47, s23, s27
	v_lshl_add_u64 v[212:213], v[134:135], 1, s[46:47]
	v_lshl_add_u64 v[212:213], v[212:213], 0, v[206:207]
	s_mov_b64 s[30:31], 0x18000
	s_mov_b64 s[34:35], 0x78000
	s_mov_b64 s[36:37], 0x8000
	s_mov_b64 s[44:45], 0x28000
	global_load_dwordx4 v[138:141], v[208:209], off offset:256
	v_lshl_add_u64 v[208:209], v[208:209], 0, s[30:31]
	global_load_dwordx4 v[142:145], v[208:209], off offset:256
	v_lshl_add_u64 v[208:209], v[208:209], 0, s[30:31]
	global_load_dwordx4 v[146:149], v[208:209], off offset:256
	v_lshl_add_u64 v[208:209], v[208:209], 0, s[30:31]
	global_load_dwordx4 v[150:153], v[208:209], off offset:256
	v_lshl_add_u64 v[208:209], v[208:209], 0, s[34:35]
	global_load_dwordx4 v[154:157], v[208:209], off offset:256
	v_lshl_add_u64 v[208:209], v[208:209], 0, s[30:31]
	global_load_dwordx4 v[158:161], v[208:209], off offset:256
	v_lshl_add_u64 v[208:209], v[208:209], 0, s[30:31]
	global_load_dwordx4 v[162:165], v[208:209], off offset:256
	v_lshl_add_u64 v[208:209], v[208:209], 0, s[30:31]
	global_load_dwordx4 v[166:169], v[208:209], off offset:256
	s_waitcnt vmcnt(7)
	v_lshlrev_b32_e32 v218, 16, v138
	v_and_b32_e32 v138, 0xffff0000, v138
	v_mul_f32_e32 v116, v116, v218
	v_mul_f32_e32 v117, v117, v138
	v_lshlrev_b32_e32 v218, 16, v139
	v_and_b32_e32 v139, 0xffff0000, v139
	v_mul_f32_e32 v118, v118, v218
	v_mul_f32_e32 v119, v119, v139
	v_lshlrev_b32_e32 v218, 16, v140
	v_and_b32_e32 v140, 0xffff0000, v140
	v_mul_f32_e32 v112, v112, v218
	v_mul_f32_e32 v113, v113, v140
	v_lshlrev_b32_e32 v218, 16, v141
	v_and_b32_e32 v141, 0xffff0000, v141
	v_mul_f32_e32 v114, v114, v218
	v_mul_f32_e32 v115, v115, v141
	v_cvt_pk_bf16_f32 v138, v116, v117
	v_cvt_pk_bf16_f32 v139, v118, v119
	v_cvt_pk_bf16_f32 v140, v112, v113
	v_cvt_pk_bf16_f32 v141, v114, v115
	global_store_dwordx4 v[212:213], v[138:141], off offset:256
	s_nop 0
	v_lshl_add_u64 v[212:213], v[212:213], 0, s[36:37]
	s_waitcnt vmcnt(7)
	v_lshlrev_b32_e32 v218, 16, v142
	v_and_b32_e32 v142, 0xffff0000, v142
	v_mul_f32_e32 v100, v100, v218
	v_mul_f32_e32 v101, v101, v142
	v_lshlrev_b32_e32 v218, 16, v143
	v_and_b32_e32 v143, 0xffff0000, v143
	v_mul_f32_e32 v102, v102, v218
	v_mul_f32_e32 v103, v103, v143
	v_lshlrev_b32_e32 v218, 16, v144
	v_and_b32_e32 v144, 0xffff0000, v144
	v_mul_f32_e32 v96, v96, v218
	v_mul_f32_e32 v97, v97, v144
	v_lshlrev_b32_e32 v218, 16, v145
	v_and_b32_e32 v145, 0xffff0000, v145
	v_mul_f32_e32 v98, v98, v218
	v_mul_f32_e32 v99, v99, v145
	v_cvt_pk_bf16_f32 v142, v100, v101
	v_cvt_pk_bf16_f32 v143, v102, v103
	v_cvt_pk_bf16_f32 v144, v96, v97
	v_cvt_pk_bf16_f32 v145, v98, v99
	global_store_dwordx4 v[212:213], v[142:145], off offset:256
	s_nop 0
	v_lshl_add_u64 v[212:213], v[212:213], 0, s[36:37]
	s_waitcnt vmcnt(7)
	v_lshlrev_b32_e32 v218, 16, v146
	v_and_b32_e32 v146, 0xffff0000, v146
	v_mul_f32_e32 v84, v84, v218
	v_mul_f32_e32 v85, v85, v146
	v_lshlrev_b32_e32 v218, 16, v147
	v_and_b32_e32 v147, 0xffff0000, v147
	v_mul_f32_e32 v86, v86, v218
	v_mul_f32_e32 v87, v87, v147
	v_lshlrev_b32_e32 v218, 16, v148
	v_and_b32_e32 v148, 0xffff0000, v148
	v_mul_f32_e32 v80, v80, v218
	v_mul_f32_e32 v81, v81, v148
	v_lshlrev_b32_e32 v218, 16, v149
	v_and_b32_e32 v149, 0xffff0000, v149
	v_mul_f32_e32 v82, v82, v218
	v_mul_f32_e32 v83, v83, v149
	v_cvt_pk_bf16_f32 v146, v84, v85
	v_cvt_pk_bf16_f32 v147, v86, v87
	v_cvt_pk_bf16_f32 v148, v80, v81
	v_cvt_pk_bf16_f32 v149, v82, v83
	global_store_dwordx4 v[212:213], v[146:149], off offset:256
	s_nop 0
	v_lshl_add_u64 v[212:213], v[212:213], 0, s[36:37]
	s_waitcnt vmcnt(7)
	v_lshlrev_b32_e32 v218, 16, v150
	v_and_b32_e32 v150, 0xffff0000, v150
	v_mul_f32_e32 v68, v68, v218
	v_mul_f32_e32 v69, v69, v150
	v_lshlrev_b32_e32 v218, 16, v151
	v_and_b32_e32 v151, 0xffff0000, v151
	v_mul_f32_e32 v70, v70, v218
	v_mul_f32_e32 v71, v71, v151
	v_lshlrev_b32_e32 v218, 16, v152
	v_and_b32_e32 v152, 0xffff0000, v152
	v_mul_f32_e32 v64, v64, v218
	v_mul_f32_e32 v65, v65, v152
	v_lshlrev_b32_e32 v218, 16, v153
	v_and_b32_e32 v153, 0xffff0000, v153
	v_mul_f32_e32 v66, v66, v218
	v_mul_f32_e32 v67, v67, v153
	v_cvt_pk_bf16_f32 v150, v68, v69
	v_cvt_pk_bf16_f32 v151, v70, v71
	v_cvt_pk_bf16_f32 v152, v64, v65
	v_cvt_pk_bf16_f32 v153, v66, v67
	global_store_dwordx4 v[212:213], v[150:153], off offset:256
	s_nop 0
	v_lshl_add_u64 v[212:213], v[212:213], 0, s[44:45]
	s_waitcnt vmcnt(7)
	v_lshlrev_b32_e32 v218, 16, v154
	v_and_b32_e32 v154, 0xffff0000, v154
	v_mul_f32_e32 v52, v52, v218
	v_mul_f32_e32 v53, v53, v154
	v_lshlrev_b32_e32 v218, 16, v155
	v_and_b32_e32 v155, 0xffff0000, v155
	v_mul_f32_e32 v54, v54, v218
	v_mul_f32_e32 v55, v55, v155
	v_lshlrev_b32_e32 v218, 16, v156
	v_and_b32_e32 v156, 0xffff0000, v156
	v_mul_f32_e32 v48, v48, v218
	v_mul_f32_e32 v49, v49, v156
	v_lshlrev_b32_e32 v218, 16, v157
	v_and_b32_e32 v157, 0xffff0000, v157
	v_mul_f32_e32 v50, v50, v218
	v_mul_f32_e32 v51, v51, v157
	v_cvt_pk_bf16_f32 v154, v52, v53
	v_cvt_pk_bf16_f32 v155, v54, v55
	v_cvt_pk_bf16_f32 v156, v48, v49
	v_cvt_pk_bf16_f32 v157, v50, v51
	global_store_dwordx4 v[212:213], v[154:157], off offset:256
	s_nop 0
	v_lshl_add_u64 v[212:213], v[212:213], 0, s[36:37]
	s_waitcnt vmcnt(7)
	v_lshlrev_b32_e32 v218, 16, v158
	v_and_b32_e32 v158, 0xffff0000, v158
	v_mul_f32_e32 v36, v36, v218
	v_mul_f32_e32 v37, v37, v158
	v_lshlrev_b32_e32 v218, 16, v159
	v_and_b32_e32 v159, 0xffff0000, v159
	v_mul_f32_e32 v38, v38, v218
	v_mul_f32_e32 v39, v39, v159
	v_lshlrev_b32_e32 v218, 16, v160
	v_and_b32_e32 v160, 0xffff0000, v160
	v_mul_f32_e32 v32, v32, v218
	v_mul_f32_e32 v33, v33, v160
	v_lshlrev_b32_e32 v218, 16, v161
	v_and_b32_e32 v161, 0xffff0000, v161
	v_mul_f32_e32 v34, v34, v218
	v_mul_f32_e32 v35, v35, v161
	v_cvt_pk_bf16_f32 v158, v36, v37
	v_cvt_pk_bf16_f32 v159, v38, v39
	v_cvt_pk_bf16_f32 v160, v32, v33
	v_cvt_pk_bf16_f32 v161, v34, v35
	global_store_dwordx4 v[212:213], v[158:161], off offset:256
	s_nop 0
	v_lshl_add_u64 v[212:213], v[212:213], 0, s[36:37]
	s_waitcnt vmcnt(7)
	v_lshlrev_b32_e32 v218, 16, v162
	v_and_b32_e32 v162, 0xffff0000, v162
	v_mul_f32_e32 v20, v20, v218
	v_mul_f32_e32 v21, v21, v162
	v_lshlrev_b32_e32 v218, 16, v163
	v_and_b32_e32 v163, 0xffff0000, v163
	v_mul_f32_e32 v22, v22, v218
	v_mul_f32_e32 v23, v23, v163
	v_lshlrev_b32_e32 v218, 16, v164
	v_and_b32_e32 v164, 0xffff0000, v164
	v_mul_f32_e32 v16, v16, v218
	v_mul_f32_e32 v17, v17, v164
	v_lshlrev_b32_e32 v218, 16, v165
	v_and_b32_e32 v165, 0xffff0000, v165
	v_mul_f32_e32 v18, v18, v218
	v_mul_f32_e32 v19, v19, v165
	v_cvt_pk_bf16_f32 v162, v20, v21
	v_cvt_pk_bf16_f32 v163, v22, v23
	v_cvt_pk_bf16_f32 v164, v16, v17
	v_cvt_pk_bf16_f32 v165, v18, v19
	global_store_dwordx4 v[212:213], v[162:165], off offset:256
	s_nop 0
	v_lshl_add_u64 v[212:213], v[212:213], 0, s[36:37]
	s_waitcnt vmcnt(7)
	v_lshlrev_b32_e32 v218, 16, v166
	v_and_b32_e32 v166, 0xffff0000, v166
	v_mul_f32_e32 v4, v4, v218
	v_mul_f32_e32 v5, v5, v166
	v_lshlrev_b32_e32 v218, 16, v167
	v_and_b32_e32 v167, 0xffff0000, v167
	v_mul_f32_e32 v6, v6, v218
	v_mul_f32_e32 v7, v7, v167
	v_lshlrev_b32_e32 v218, 16, v168
	v_and_b32_e32 v168, 0xffff0000, v168
	v_mul_f32_e32 v0, v0, v218
	v_mul_f32_e32 v1, v1, v168
	v_lshlrev_b32_e32 v218, 16, v169
	v_and_b32_e32 v169, 0xffff0000, v169
	v_mul_f32_e32 v2, v2, v218
	v_mul_f32_e32 v3, v3, v169
	v_cvt_pk_bf16_f32 v166, v4, v5
	v_cvt_pk_bf16_f32 v167, v6, v7
	v_cvt_pk_bf16_f32 v168, v0, v1
	v_cvt_pk_bf16_f32 v169, v2, v3
	global_store_dwordx4 v[212:213], v[166:169], off offset:256
	s_branch .LBB0_1411
.Lpc1_fast_b1t:
	v_lshlrev_b64 v[206:207], 1, v[130:131]
	v_lshl_add_u64 v[208:209], s[24:25], 0, v[136:137]
	v_lshl_add_u64 v[208:209], s[54:55], 1, v[208:209]
	v_lshl_add_u64 v[208:209], v[208:209], 0, v[206:207]
	v_lshl_add_u64 v[210:211], v[134:135], 1, s[22:23]
	v_lshl_add_u64 v[210:211], v[210:211], 0, v[206:207]
	s_and_b64 s[36:37], s[50:51], exec
	s_cselect_b32 s46, s22, s26
	s_cselect_b32 s47, s23, s27
	v_lshl_add_u64 v[212:213], v[134:135], 1, s[46:47]
	v_lshl_add_u64 v[212:213], v[212:213], 0, v[206:207]
	s_mov_b64 s[30:31], 0x18000
	s_mov_b64 s[34:35], 0x78000
	s_mov_b64 s[36:37], 0x8000
	s_mov_b64 s[44:45], 0x28000
	global_load_dwordx4 v[138:141], v[208:209], off offset:256
	global_load_dwordx4 v[170:173], v[210:211], off offset:256
	v_lshl_add_u64 v[208:209], v[208:209], 0, s[30:31]
	v_lshl_add_u64 v[210:211], v[210:211], 0, s[36:37]
	global_load_dwordx4 v[142:145], v[208:209], off offset:256
	global_load_dwordx4 v[174:177], v[210:211], off offset:256
	v_lshl_add_u64 v[208:209], v[208:209], 0, s[30:31]
	v_lshl_add_u64 v[210:211], v[210:211], 0, s[36:37]
	global_load_dwordx4 v[146:149], v[208:209], off offset:256
	global_load_dwordx4 v[178:181], v[210:211], off offset:256
	v_lshl_add_u64 v[208:209], v[208:209], 0, s[30:31]
	v_lshl_add_u64 v[210:211], v[210:211], 0, s[36:37]
	global_load_dwordx4 v[150:153], v[208:209], off offset:256
	global_load_dwordx4 v[182:185], v[210:211], off offset:256
	v_lshl_add_u64 v[208:209], v[208:209], 0, s[34:35]
	v_lshl_add_u64 v[210:211], v[210:211], 0, s[44:45]
	global_load_dwordx4 v[154:157], v[208:209], off offset:256
	global_load_dwordx4 v[186:189], v[210:211], off offset:256
	v_lshl_add_u64 v[208:209], v[208:209], 0, s[30:31]
	v_lshl_add_u64 v[210:211], v[210:211], 0, s[36:37]
	global_load_dwordx4 v[158:161], v[208:209], off offset:256
	global_load_dwordx4 v[190:193], v[210:211], off offset:256
	v_lshl_add_u64 v[208:209], v[208:209], 0, s[30:31]
	v_lshl_add_u64 v[210:211], v[210:211], 0, s[36:37]
	global_load_dwordx4 v[162:165], v[208:209], off offset:256
	global_load_dwordx4 v[130:133], v[210:211], off offset:256
	v_lshl_add_u64 v[208:209], v[208:209], 0, s[30:31]
	v_lshl_add_u64 v[210:211], v[210:211], 0, s[36:37]
	global_load_dwordx4 v[166:169], v[208:209], off offset:256
	global_load_dwordx4 v[134:137], v[210:211], off offset:256
	s_waitcnt vmcnt(14)
	v_lshlrev_b32_e32 v218, 16, v138
	v_and_b32_e32 v138, 0xffff0000, v138
	v_mul_f32_e32 v116, v116, v218
	v_mul_f32_e32 v117, v117, v138
	v_lshlrev_b32_e32 v218, 16, v139
	v_and_b32_e32 v139, 0xffff0000, v139
	v_mul_f32_e32 v118, v118, v218
	v_mul_f32_e32 v119, v119, v139
	v_lshlrev_b32_e32 v218, 16, v140
	v_and_b32_e32 v140, 0xffff0000, v140
	v_mul_f32_e32 v112, v112, v218
	v_mul_f32_e32 v113, v113, v140
	v_lshlrev_b32_e32 v218, 16, v141
	v_and_b32_e32 v141, 0xffff0000, v141
	v_mul_f32_e32 v114, v114, v218
	v_mul_f32_e32 v115, v115, v141
	v_lshlrev_b32_e32 v219, 16, v170
	v_and_b32_e32 v170, 0xffff0000, v170
	v_add_f32_e32 v116, v116, v219
	v_add_f32_e32 v117, v117, v170
	v_lshlrev_b32_e32 v219, 16, v171
	v_and_b32_e32 v171, 0xffff0000, v171
	v_add_f32_e32 v118, v118, v219
	v_add_f32_e32 v119, v119, v171
	v_lshlrev_b32_e32 v219, 16, v172
	v_and_b32_e32 v172, 0xffff0000, v172
	v_add_f32_e32 v112, v112, v219
	v_add_f32_e32 v113, v113, v172
	v_lshlrev_b32_e32 v219, 16, v173
	v_and_b32_e32 v173, 0xffff0000, v173
	v_add_f32_e32 v114, v114, v219
	v_add_f32_e32 v115, v115, v173
	v_cvt_pk_bf16_f32 v138, v116, v117
	v_cvt_pk_bf16_f32 v139, v118, v119
	v_cvt_pk_bf16_f32 v140, v112, v113
	v_cvt_pk_bf16_f32 v141, v114, v115
	global_store_dwordx4 v[212:213], v[138:141], off offset:256
	s_nop 0
	v_lshl_add_u64 v[212:213], v[212:213], 0, s[36:37]
	s_waitcnt vmcnt(13)
	v_lshlrev_b32_e32 v218, 16, v142
	v_and_b32_e32 v142, 0xffff0000, v142
	v_mul_f32_e32 v100, v100, v218
	v_mul_f32_e32 v101, v101, v142
	v_lshlrev_b32_e32 v218, 16, v143
	v_and_b32_e32 v143, 0xffff0000, v143
	v_mul_f32_e32 v102, v102, v218
	v_mul_f32_e32 v103, v103, v143
	v_lshlrev_b32_e32 v218, 16, v144
	v_and_b32_e32 v144, 0xffff0000, v144
	v_mul_f32_e32 v96, v96, v218
	v_mul_f32_e32 v97, v97, v144
	v_lshlrev_b32_e32 v218, 16, v145
	v_and_b32_e32 v145, 0xffff0000, v145
	v_mul_f32_e32 v98, v98, v218
	v_mul_f32_e32 v99, v99, v145
	v_lshlrev_b32_e32 v219, 16, v174
	v_and_b32_e32 v174, 0xffff0000, v174
	v_add_f32_e32 v100, v100, v219
	v_add_f32_e32 v101, v101, v174
	v_lshlrev_b32_e32 v219, 16, v175
	v_and_b32_e32 v175, 0xffff0000, v175
	v_add_f32_e32 v102, v102, v219
	v_add_f32_e32 v103, v103, v175
	v_lshlrev_b32_e32 v219, 16, v176
	v_and_b32_e32 v176, 0xffff0000, v176
	v_add_f32_e32 v96, v96, v219
	v_add_f32_e32 v97, v97, v176
	v_lshlrev_b32_e32 v219, 16, v177
	v_and_b32_e32 v177, 0xffff0000, v177
	v_add_f32_e32 v98, v98, v219
	v_add_f32_e32 v99, v99, v177
	v_cvt_pk_bf16_f32 v142, v100, v101
	v_cvt_pk_bf16_f32 v143, v102, v103
	v_cvt_pk_bf16_f32 v144, v96, v97
	v_cvt_pk_bf16_f32 v145, v98, v99
	global_store_dwordx4 v[212:213], v[142:145], off offset:256
	s_nop 0
	v_lshl_add_u64 v[212:213], v[212:213], 0, s[36:37]
	s_waitcnt vmcnt(12)
	v_lshlrev_b32_e32 v218, 16, v146
	v_and_b32_e32 v146, 0xffff0000, v146
	v_mul_f32_e32 v84, v84, v218
	v_mul_f32_e32 v85, v85, v146
	v_lshlrev_b32_e32 v218, 16, v147
	v_and_b32_e32 v147, 0xffff0000, v147
	v_mul_f32_e32 v86, v86, v218
	v_mul_f32_e32 v87, v87, v147
	v_lshlrev_b32_e32 v218, 16, v148
	v_and_b32_e32 v148, 0xffff0000, v148
	v_mul_f32_e32 v80, v80, v218
	v_mul_f32_e32 v81, v81, v148
	v_lshlrev_b32_e32 v218, 16, v149
	v_and_b32_e32 v149, 0xffff0000, v149
	v_mul_f32_e32 v82, v82, v218
	v_mul_f32_e32 v83, v83, v149
	v_lshlrev_b32_e32 v219, 16, v178
	v_and_b32_e32 v178, 0xffff0000, v178
	v_add_f32_e32 v84, v84, v219
	v_add_f32_e32 v85, v85, v178
	v_lshlrev_b32_e32 v219, 16, v179
	v_and_b32_e32 v179, 0xffff0000, v179
	v_add_f32_e32 v86, v86, v219
	v_add_f32_e32 v87, v87, v179
	v_lshlrev_b32_e32 v219, 16, v180
	v_and_b32_e32 v180, 0xffff0000, v180
	v_add_f32_e32 v80, v80, v219
	v_add_f32_e32 v81, v81, v180
	v_lshlrev_b32_e32 v219, 16, v181
	v_and_b32_e32 v181, 0xffff0000, v181
	v_add_f32_e32 v82, v82, v219
	v_add_f32_e32 v83, v83, v181
	v_cvt_pk_bf16_f32 v146, v84, v85
	v_cvt_pk_bf16_f32 v147, v86, v87
	v_cvt_pk_bf16_f32 v148, v80, v81
	v_cvt_pk_bf16_f32 v149, v82, v83
	global_store_dwordx4 v[212:213], v[146:149], off offset:256
	s_nop 0
	v_lshl_add_u64 v[212:213], v[212:213], 0, s[36:37]
	s_waitcnt vmcnt(11)
	v_lshlrev_b32_e32 v218, 16, v150
	v_and_b32_e32 v150, 0xffff0000, v150
	v_mul_f32_e32 v68, v68, v218
	v_mul_f32_e32 v69, v69, v150
	v_lshlrev_b32_e32 v218, 16, v151
	v_and_b32_e32 v151, 0xffff0000, v151
	v_mul_f32_e32 v70, v70, v218
	v_mul_f32_e32 v71, v71, v151
	v_lshlrev_b32_e32 v218, 16, v152
	v_and_b32_e32 v152, 0xffff0000, v152
	v_mul_f32_e32 v64, v64, v218
	v_mul_f32_e32 v65, v65, v152
	v_lshlrev_b32_e32 v218, 16, v153
	v_and_b32_e32 v153, 0xffff0000, v153
	v_mul_f32_e32 v66, v66, v218
	v_mul_f32_e32 v67, v67, v153
	v_lshlrev_b32_e32 v219, 16, v182
	v_and_b32_e32 v182, 0xffff0000, v182
	v_add_f32_e32 v68, v68, v219
	v_add_f32_e32 v69, v69, v182
	v_lshlrev_b32_e32 v219, 16, v183
	v_and_b32_e32 v183, 0xffff0000, v183
	v_add_f32_e32 v70, v70, v219
	v_add_f32_e32 v71, v71, v183
	v_lshlrev_b32_e32 v219, 16, v184
	v_and_b32_e32 v184, 0xffff0000, v184
	v_add_f32_e32 v64, v64, v219
	v_add_f32_e32 v65, v65, v184
	v_lshlrev_b32_e32 v219, 16, v185
	v_and_b32_e32 v185, 0xffff0000, v185
	v_add_f32_e32 v66, v66, v219
	v_add_f32_e32 v67, v67, v185
	v_cvt_pk_bf16_f32 v150, v68, v69
	v_cvt_pk_bf16_f32 v151, v70, v71
	v_cvt_pk_bf16_f32 v152, v64, v65
	v_cvt_pk_bf16_f32 v153, v66, v67
	global_store_dwordx4 v[212:213], v[150:153], off offset:256
	s_nop 0
	v_lshl_add_u64 v[212:213], v[212:213], 0, s[44:45]
	s_waitcnt vmcnt(10)
	v_lshlrev_b32_e32 v218, 16, v154
	v_and_b32_e32 v154, 0xffff0000, v154
	v_mul_f32_e32 v52, v52, v218
	v_mul_f32_e32 v53, v53, v154
	v_lshlrev_b32_e32 v218, 16, v155
	v_and_b32_e32 v155, 0xffff0000, v155
	v_mul_f32_e32 v54, v54, v218
	v_mul_f32_e32 v55, v55, v155
	v_lshlrev_b32_e32 v218, 16, v156
	v_and_b32_e32 v156, 0xffff0000, v156
	v_mul_f32_e32 v48, v48, v218
	v_mul_f32_e32 v49, v49, v156
	v_lshlrev_b32_e32 v218, 16, v157
	v_and_b32_e32 v157, 0xffff0000, v157
	v_mul_f32_e32 v50, v50, v218
	v_mul_f32_e32 v51, v51, v157
	v_lshlrev_b32_e32 v219, 16, v186
	v_and_b32_e32 v186, 0xffff0000, v186
	v_add_f32_e32 v52, v52, v219
	v_add_f32_e32 v53, v53, v186
	v_lshlrev_b32_e32 v219, 16, v187
	v_and_b32_e32 v187, 0xffff0000, v187
	v_add_f32_e32 v54, v54, v219
	v_add_f32_e32 v55, v55, v187
	v_lshlrev_b32_e32 v219, 16, v188
	v_and_b32_e32 v188, 0xffff0000, v188
	v_add_f32_e32 v48, v48, v219
	v_add_f32_e32 v49, v49, v188
	v_lshlrev_b32_e32 v219, 16, v189
	v_and_b32_e32 v189, 0xffff0000, v189
	v_add_f32_e32 v50, v50, v219
	v_add_f32_e32 v51, v51, v189
	v_cvt_pk_bf16_f32 v154, v52, v53
	v_cvt_pk_bf16_f32 v155, v54, v55
	v_cvt_pk_bf16_f32 v156, v48, v49
	v_cvt_pk_bf16_f32 v157, v50, v51
	global_store_dwordx4 v[212:213], v[154:157], off offset:256
	s_nop 0
	v_lshl_add_u64 v[212:213], v[212:213], 0, s[36:37]
	s_waitcnt vmcnt(9)
	v_lshlrev_b32_e32 v218, 16, v158
	v_and_b32_e32 v158, 0xffff0000, v158
	v_mul_f32_e32 v36, v36, v218
	v_mul_f32_e32 v37, v37, v158
	v_lshlrev_b32_e32 v218, 16, v159
	v_and_b32_e32 v159, 0xffff0000, v159
	v_mul_f32_e32 v38, v38, v218
	v_mul_f32_e32 v39, v39, v159
	v_lshlrev_b32_e32 v218, 16, v160
	v_and_b32_e32 v160, 0xffff0000, v160
	v_mul_f32_e32 v32, v32, v218
	v_mul_f32_e32 v33, v33, v160
	v_lshlrev_b32_e32 v218, 16, v161
	v_and_b32_e32 v161, 0xffff0000, v161
	v_mul_f32_e32 v34, v34, v218
	v_mul_f32_e32 v35, v35, v161
	v_lshlrev_b32_e32 v219, 16, v190
	v_and_b32_e32 v190, 0xffff0000, v190
	v_add_f32_e32 v36, v36, v219
	v_add_f32_e32 v37, v37, v190
	v_lshlrev_b32_e32 v219, 16, v191
	v_and_b32_e32 v191, 0xffff0000, v191
	v_add_f32_e32 v38, v38, v219
	v_add_f32_e32 v39, v39, v191
	v_lshlrev_b32_e32 v219, 16, v192
	v_and_b32_e32 v192, 0xffff0000, v192
	v_add_f32_e32 v32, v32, v219
	v_add_f32_e32 v33, v33, v192
	v_lshlrev_b32_e32 v219, 16, v193
	v_and_b32_e32 v193, 0xffff0000, v193
	v_add_f32_e32 v34, v34, v219
	v_add_f32_e32 v35, v35, v193
	v_cvt_pk_bf16_f32 v158, v36, v37
	v_cvt_pk_bf16_f32 v159, v38, v39
	v_cvt_pk_bf16_f32 v160, v32, v33
	v_cvt_pk_bf16_f32 v161, v34, v35
	global_store_dwordx4 v[212:213], v[158:161], off offset:256
	s_nop 0
	v_lshl_add_u64 v[212:213], v[212:213], 0, s[36:37]
	s_waitcnt vmcnt(8)
	v_lshlrev_b32_e32 v218, 16, v162
	v_and_b32_e32 v162, 0xffff0000, v162
	v_mul_f32_e32 v20, v20, v218
	v_mul_f32_e32 v21, v21, v162
	v_lshlrev_b32_e32 v218, 16, v163
	v_and_b32_e32 v163, 0xffff0000, v163
	v_mul_f32_e32 v22, v22, v218
	v_mul_f32_e32 v23, v23, v163
	v_lshlrev_b32_e32 v218, 16, v164
	v_and_b32_e32 v164, 0xffff0000, v164
	v_mul_f32_e32 v16, v16, v218
	v_mul_f32_e32 v17, v17, v164
	v_lshlrev_b32_e32 v218, 16, v165
	v_and_b32_e32 v165, 0xffff0000, v165
	v_mul_f32_e32 v18, v18, v218
	v_mul_f32_e32 v19, v19, v165
	v_lshlrev_b32_e32 v219, 16, v130
	v_and_b32_e32 v130, 0xffff0000, v130
	v_add_f32_e32 v20, v20, v219
	v_add_f32_e32 v21, v21, v130
	v_lshlrev_b32_e32 v219, 16, v131
	v_and_b32_e32 v131, 0xffff0000, v131
	v_add_f32_e32 v22, v22, v219
	v_add_f32_e32 v23, v23, v131
	v_lshlrev_b32_e32 v219, 16, v132
	v_and_b32_e32 v132, 0xffff0000, v132
	v_add_f32_e32 v16, v16, v219
	v_add_f32_e32 v17, v17, v132
	v_lshlrev_b32_e32 v219, 16, v133
	v_and_b32_e32 v133, 0xffff0000, v133
	v_add_f32_e32 v18, v18, v219
	v_add_f32_e32 v19, v19, v133
	v_cvt_pk_bf16_f32 v162, v20, v21
	v_cvt_pk_bf16_f32 v163, v22, v23
	v_cvt_pk_bf16_f32 v164, v16, v17
	v_cvt_pk_bf16_f32 v165, v18, v19
	global_store_dwordx4 v[212:213], v[162:165], off offset:256
	s_nop 0
	v_lshl_add_u64 v[212:213], v[212:213], 0, s[36:37]
	s_waitcnt vmcnt(7)
	v_lshlrev_b32_e32 v218, 16, v166
	v_and_b32_e32 v166, 0xffff0000, v166
	v_mul_f32_e32 v4, v4, v218
	v_mul_f32_e32 v5, v5, v166
	v_lshlrev_b32_e32 v218, 16, v167
	v_and_b32_e32 v167, 0xffff0000, v167
	v_mul_f32_e32 v6, v6, v218
	v_mul_f32_e32 v7, v7, v167
	v_lshlrev_b32_e32 v218, 16, v168
	v_and_b32_e32 v168, 0xffff0000, v168
	v_mul_f32_e32 v0, v0, v218
	v_mul_f32_e32 v1, v1, v168
	v_lshlrev_b32_e32 v218, 16, v169
	v_and_b32_e32 v169, 0xffff0000, v169
	v_mul_f32_e32 v2, v2, v218
	v_mul_f32_e32 v3, v3, v169
	v_lshlrev_b32_e32 v219, 16, v134
	v_and_b32_e32 v134, 0xffff0000, v134
	v_add_f32_e32 v4, v4, v219
	v_add_f32_e32 v5, v5, v134
	v_lshlrev_b32_e32 v219, 16, v135
	v_and_b32_e32 v135, 0xffff0000, v135
	v_add_f32_e32 v6, v6, v219
	v_add_f32_e32 v7, v7, v135
	v_lshlrev_b32_e32 v219, 16, v136
	v_and_b32_e32 v136, 0xffff0000, v136
	v_add_f32_e32 v0, v0, v219
	v_add_f32_e32 v1, v1, v136
	v_lshlrev_b32_e32 v219, 16, v137
	v_and_b32_e32 v137, 0xffff0000, v137
	v_add_f32_e32 v2, v2, v219
	v_add_f32_e32 v3, v3, v137
	v_cvt_pk_bf16_f32 v166, v4, v5
	v_cvt_pk_bf16_f32 v167, v6, v7
	v_cvt_pk_bf16_f32 v168, v0, v1
	v_cvt_pk_bf16_f32 v169, v2, v3
	global_store_dwordx4 v[212:213], v[166:169], off offset:256
	s_branch .LBB0_1411
.Lpc1_old:
	s_cbranch_vccnz .LBB0_1306
	v_lshl_add_u64 v[138:139], s[24:25], 0, v[136:137]
	v_lshl_add_u64 v[138:139], s[54:55], 1, v[138:139]
	v_lshlrev_b64 v[142:143], 1, v[130:131]
	v_lshl_add_u64 v[138:139], v[138:139], 0, v[142:143]
	global_load_dwordx4 v[138:141], v[138:139], off
	s_and_b64 vcc, exec, s[44:45]
	s_waitcnt vmcnt(0)
	v_lshlrev_b32_e32 v144, 16, v138
	v_and_b32_e32 v145, 0xffff0000, v138
	v_lshlrev_b32_e32 v138, 16, v139
	v_and_b32_e32 v139, 0xffff0000, v139
	v_lshlrev_b32_e32 v146, 16, v140
	v_and_b32_e32 v147, 0xffff0000, v140
	v_lshlrev_b32_e32 v140, 16, v141
	v_and_b32_e32 v141, 0xffff0000, v141
	v_pk_mul_f32 v[126:127], v[126:127], v[138:139]
	v_pk_mul_f32 v[138:139], v[124:125], v[144:145]
	v_pk_mul_f32 v[124:125], v[122:123], v[140:141]
	v_pk_mul_f32 v[122:123], v[120:121], v[146:147]
	v_lshl_add_u64 v[120:121], v[134:135], 1, s[22:23]
	v_lshl_add_u64 v[140:141], v[120:121], 0, v[142:143]
	s_cbranch_vccnz .LBB0_1302
	global_load_dwordx4 v[142:145], v[140:141], off
	s_waitcnt vmcnt(0)
	v_lshlrev_b32_e32 v120, 16, v142
	v_and_b32_e32 v121, 0xffff0000, v142
	v_pk_add_f32 v[138:139], v[138:139], v[120:121]
	v_lshlrev_b32_e32 v120, 16, v143
	v_and_b32_e32 v121, 0xffff0000, v143
	v_pk_add_f32 v[126:127], v[126:127], v[120:121]
	v_lshlrev_b32_e32 v120, 16, v144
	v_and_b32_e32 v121, 0xffff0000, v144
	v_pk_add_f32 v[122:123], v[122:123], v[120:121]
	v_lshlrev_b32_e32 v120, 16, v145
	v_and_b32_e32 v121, 0xffff0000, v145
	v_pk_add_f32 v[124:125], v[124:125], v[120:121]
